# phase 8 rows and phase 6 stash remapped per XCD (rows a XCD's own tiles wrote are normalised on that XCD; stash regions aligned with the XCD's x1 rows)
# speedup vs baseline: 1.0042x; 1.0042x over previous
.Lp6_dec:
	s_load_dwordx2 s[22:23], s[0:1], 0x60
	s_load_dwordx2 s[24:25], s[0:1], 0xe0
	s_load_dwordx2 s[26:27], s[0:1], 0xd8
	s_mov_b32 s3, 0x7fff
	v_mov_b32_e32 v242, 1
	v_lshlrev_b32_e32 v243, 4, v168
	v_bfe_u32 v249, v168, 6, 1
	v_bfe_u32 v250, v168, 4, 2
	v_lshlrev_b32_e32 v250, 4, v250
	v_lshl_or_b32 v244, v249, 8, v250
	s_lshl_b32 s71, s74, 9
	s_and_b32 s72, s2, 7
	s_lshl_b32 s72, s72, 23
	s_lshr_b32 s73, s2, 3
	s_lshl_b32 s73, s73, 17
	s_add_u32 s72, s72, s73
	s_waitcnt lgkmcnt(0)
	s_add_u32 s22, s22, s71
	s_addc_u32 s23, s23, 0
	s_add_u32 s24, s24, s72
	s_addc_u32 s25, s25, 0
	v_and_b32_e32 v236, 15, v168
	v_lshrrev_b32_e32 v237, 1, v236
	v_bfe_u32 v238, v168, 4, 2
	v_xor_b32_e32 v237, v237, v238
	v_lshlrev_b32_e32 v237, 4, v237
	v_lshl_or_b32 v236, v236, 7, v237
	v_xor_b32_e32 v237, 64, v236
	v_add_u32_e32 v236, 16, v236
	v_add_u32_e32 v237, 16, v237
	v_bfe_u32 v238, v168, 7, 1
	v_lshl_add_u32 v240, v238, 13, v237
	v_lshl_add_u32 v238, v238, 13, v236
	v_bfe_u32 v239, v168, 6, 1
	v_lshl_add_u32 v241, v239, 13, v237
	v_lshl_add_u32 v239, v239, 13, v236
	v_lshrrev_b32_e32 v236, 3, v168
	v_lshrrev_b32_e32 v237, 4, v168
	v_xor_b32_e32 v237, v237, v168
	v_and_b32_e32 v237, 7, v237
	v_lshlrev_b32_e32 v237, 4, v237
	v_lshl_or_b32 v232, v236, 11, v237
	v_add_u32_e32 v233, 0x10000, v232
	v_add_u32_e32 v234, 0x20000, v232
	v_add_u32_e32 v235, 0x30000, v232
	s_load_dwordx2 s[90:91], s[0:1], 0xa0
	s_load_dwordx2 s[92:93], s[0:1], 0xa8
	v_lshrrev_b32_e32 v237, 6, v168
	s_nop 1
	v_readfirstlane_b32 s97, v237
	s_nop 3
	s_lshl_b32 s96, s97, 10
	s_add_u32 s96, s96, 16
	s_add_u32 s94, s81, s80
	s_cmp_lt_i32 s94, s82
	s_cselect_b32 s95, 1, 0
	s_cmp_lg_u64 s[20:21], 0
	s_cselect_b32 s95, 0, s95
	s_cmp_ge_u32 s94, 0x40
	s_cselect_b32 s97, 1, 0
	s_mul_i32 s100, s97, 0x40
	s_sub_u32 s100, s94, s100
	s_lshr_b32 s101, s100, 3
	s_and_b32 s100, s100, 7
	s_lshl_b32 s97, s97, 3
	s_add_u32 s100, s100, s97
	s_add_u32 s100, s100, s79
	s_cmp_lg_u32 s101, s74
	s_cselect_b32 s95, 0, s95
	s_cmp_eq_u32 s95, 1
	s_cselect_b32 s101, s100, s70
	s_mov_b32 s97, s101
	s_waitcnt lgkmcnt(0)
	s_lshl_b32 s94, s74, 18
	s_add_u32 s94, s94, 0xc40000
	s_add_u32 s98, s92, s94
	s_addc_u32 s99, s93, 0
	s_lshl_b32 s101, s101, 18
	s_add_u32 s92, s90, s101
	s_addc_u32 s93, s91, 0
	s_lshl_b32 s94, s70, 18
	s_add_u32 s90, s90, s94
	s_addc_u32 s91, s91, 0
	s_mov_b64 s[100:101], s[90:91]
	s_mov_b64 s[90:91], s[98:99]
	s_mov_b64 s[98:99], s[92:93]
	s_mov_b64 s[92:93], s[100:101]
	s_waitcnt vmcnt(0)
	s_barrier
	s_add_u32 m0, s96, 0x0
	s_nop 0
	global_load_lds_dwordx4 v232, s[90:91]
	s_add_u32 m0, s96, 0x1000
	s_nop 0
	global_load_lds_dwordx4 v233, s[90:91]
	s_add_u32 m0, s96, 0x2000
	s_nop 0
	global_load_lds_dwordx4 v234, s[90:91]
	s_add_u32 m0, s96, 0x3000
	s_nop 0
	global_load_lds_dwordx4 v235, s[90:91]
	s_add_u32 m0, s96, 0x8000
	s_nop 0
	global_load_lds_dwordx4 v232, s[92:93]
	s_add_u32 m0, s96, 0x9000
	s_nop 0
	global_load_lds_dwordx4 v233, s[92:93]
	s_add_u32 m0, s96, 0xa000
	s_nop 0
	global_load_lds_dwordx4 v234, s[92:93]
	s_add_u32 m0, s96, 0xb000
	s_nop 0
	global_load_lds_dwordx4 v235, s[92:93]
	s_add_u32 m0, s96, 0xc000
	s_nop 0
	global_load_lds_dwordx4 v232, s[98:99]
	s_add_u32 m0, s96, 0xd000
	s_nop 0
	global_load_lds_dwordx4 v233, s[98:99]
	s_add_u32 m0, s96, 0xe000
	s_nop 0
	global_load_lds_dwordx4 v234, s[98:99]
	s_add_u32 m0, s96, 0xf000
	s_nop 0
	global_load_lds_dwordx4 v235, s[98:99]
	s_add_u32 s90, s90, 0x80
	s_addc_u32 s91, s91, 0
	s_add_u32 s92, s92, 0x80
	s_addc_u32 s93, s93, 0
	s_add_u32 s98, s98, 0x80
	s_addc_u32 s99, s99, 0
	v_mov_b32_e32 v0, 0
	v_mov_b32_e32 v1, v0
	v_mov_b32_e32 v2, v0
	v_mov_b32_e32 v3, v0
	v_mov_b32_e32 v4, v0
	v_mov_b32_e32 v5, v0
	v_mov_b32_e32 v6, v0
	v_mov_b32_e32 v7, v0
	v_mov_b32_e32 v8, v0
	v_mov_b32_e32 v9, v0
	v_mov_b32_e32 v10, v0
	v_mov_b32_e32 v11, v0
	v_mov_b32_e32 v12, v0
	v_mov_b32_e32 v13, v0
	v_mov_b32_e32 v14, v0
	v_mov_b32_e32 v15, v0
	v_mov_b32_e32 v16, v0
	v_mov_b32_e32 v17, v0
	v_mov_b32_e32 v18, v0
	v_mov_b32_e32 v19, v0
	v_mov_b32_e32 v20, v0
	v_mov_b32_e32 v21, v0
	v_mov_b32_e32 v22, v0
	v_mov_b32_e32 v23, v0
	v_mov_b32_e32 v24, v0
	v_mov_b32_e32 v25, v0
	v_mov_b32_e32 v26, v0
	v_mov_b32_e32 v27, v0
	v_mov_b32_e32 v28, v0
	v_mov_b32_e32 v29, v0
	v_mov_b32_e32 v30, v0
	v_mov_b32_e32 v31, v0
	v_mov_b32_e32 v32, v0
	v_mov_b32_e32 v33, v0
	v_mov_b32_e32 v34, v0
	v_mov_b32_e32 v35, v0
	v_mov_b32_e32 v36, v0
	v_mov_b32_e32 v37, v0
	v_mov_b32_e32 v38, v0
	v_mov_b32_e32 v39, v0
	v_mov_b32_e32 v40, v0
	v_mov_b32_e32 v41, v0
	v_mov_b32_e32 v42, v0
	v_mov_b32_e32 v43, v0
	v_mov_b32_e32 v44, v0
	v_mov_b32_e32 v45, v0
	v_mov_b32_e32 v46, v0
	v_mov_b32_e32 v47, v0
	v_mov_b32_e32 v48, v0
	v_mov_b32_e32 v49, v0
	v_mov_b32_e32 v50, v0
	v_mov_b32_e32 v51, v0
	v_mov_b32_e32 v52, v0
	v_mov_b32_e32 v53, v0
	v_mov_b32_e32 v54, v0
	v_mov_b32_e32 v55, v0
	v_mov_b32_e32 v56, v0
	v_mov_b32_e32 v57, v0
	v_mov_b32_e32 v58, v0
	v_mov_b32_e32 v59, v0
	v_mov_b32_e32 v60, v0
	v_mov_b32_e32 v61, v0
	v_mov_b32_e32 v62, v0
	v_mov_b32_e32 v63, v0
	v_mov_b32_e32 v64, v0
	v_mov_b32_e32 v65, v0
	v_mov_b32_e32 v66, v0
	v_mov_b32_e32 v67, v0
	v_mov_b32_e32 v68, v0
	v_mov_b32_e32 v69, v0
	v_mov_b32_e32 v70, v0
	v_mov_b32_e32 v71, v0
	v_mov_b32_e32 v72, v0
	v_mov_b32_e32 v73, v0
	v_mov_b32_e32 v74, v0
	v_mov_b32_e32 v75, v0
	v_mov_b32_e32 v76, v0
	v_mov_b32_e32 v77, v0
	v_mov_b32_e32 v78, v0
	v_mov_b32_e32 v79, v0
	v_mov_b32_e32 v80, v0
	v_mov_b32_e32 v81, v0
	v_mov_b32_e32 v82, v0
	v_mov_b32_e32 v83, v0
	v_mov_b32_e32 v84, v0
	v_mov_b32_e32 v85, v0
	v_mov_b32_e32 v86, v0
	v_mov_b32_e32 v87, v0
	v_mov_b32_e32 v88, v0
	v_mov_b32_e32 v89, v0
	v_mov_b32_e32 v90, v0
	v_mov_b32_e32 v91, v0
	v_mov_b32_e32 v92, v0
	v_mov_b32_e32 v93, v0
	v_mov_b32_e32 v94, v0
	v_mov_b32_e32 v95, v0
	v_mov_b32_e32 v96, v0
	v_mov_b32_e32 v97, v0
	v_mov_b32_e32 v98, v0
	v_mov_b32_e32 v99, v0
	v_mov_b32_e32 v100, v0
	v_mov_b32_e32 v101, v0
	v_mov_b32_e32 v102, v0
	v_mov_b32_e32 v103, v0
	v_mov_b32_e32 v104, v0
	v_mov_b32_e32 v105, v0
	v_mov_b32_e32 v106, v0
	v_mov_b32_e32 v107, v0
	v_mov_b32_e32 v108, v0
	v_mov_b32_e32 v109, v0
	v_mov_b32_e32 v110, v0
	v_mov_b32_e32 v111, v0
	v_mov_b32_e32 v112, v0
	v_mov_b32_e32 v113, v0
	v_mov_b32_e32 v114, v0
	v_mov_b32_e32 v115, v0
	v_mov_b32_e32 v116, v0
	v_mov_b32_e32 v117, v0
	v_mov_b32_e32 v118, v0
	v_mov_b32_e32 v119, v0
	v_mov_b32_e32 v120, v0
	v_mov_b32_e32 v121, v0
	v_mov_b32_e32 v122, v0
	v_mov_b32_e32 v123, v0
	v_mov_b32_e32 v124, v0
	v_mov_b32_e32 v125, v0
	v_mov_b32_e32 v126, v0
	v_mov_b32_e32 v127, v0
	s_mov_b32 s94, 0

.Lp6a_ep:
	global_load_dwordx4 v[128:131], v244, s[22:23]
	global_load_dwordx4 v[132:135], v244, s[22:23] offset:64
	global_load_dwordx4 v[136:139], v244, s[22:23] offset:128
	global_load_dwordx4 v[140:143], v244, s[22:23] offset:192
	s_lshl_b32 s71, s83, 16
	s_add_u32 s84, s24, s71
	s_addc_u32 s85, s25, 0
	s_waitcnt vmcnt(0)
	v_add_f32_e32 v148, v0, v128
	v_add_f32_e32 v149, v1, v129
	v_add_f32_e32 v150, v2, v130
	v_add_f32_e32 v151, v3, v131
	v_add_f32_e32 v152, v4, v132
	v_add_f32_e32 v153, v5, v133
	v_add_f32_e32 v154, v6, v134
	v_add_f32_e32 v155, v7, v135
	v_mul_f32_e32 v148, 0xbfb8aa3b, v148
	v_mul_f32_e32 v149, 0xbfb8aa3b, v149
	v_mul_f32_e32 v150, 0xbfb8aa3b, v150
	v_mul_f32_e32 v151, 0xbfb8aa3b, v151
	v_mul_f32_e32 v152, 0xbfb8aa3b, v152
	v_mul_f32_e32 v153, 0xbfb8aa3b, v153
	v_mul_f32_e32 v154, 0xbfb8aa3b, v154
	v_mul_f32_e32 v155, 0xbfb8aa3b, v155
	v_exp_f32_e32 v156, v148
	v_exp_f32_e32 v157, v149
	v_exp_f32_e32 v158, v150
	v_exp_f32_e32 v159, v151
	v_exp_f32_e32 v160, v152
	v_exp_f32_e32 v161, v153
	v_exp_f32_e32 v162, v154
	v_exp_f32_e32 v163, v155
	v_add_f32_e32 v156, 1.0, v156
	v_add_f32_e32 v157, 1.0, v157
	v_add_f32_e32 v158, 1.0, v158
	v_add_f32_e32 v159, 1.0, v159
	v_add_f32_e32 v160, 1.0, v160
	v_add_f32_e32 v161, 1.0, v161
	v_add_f32_e32 v162, 1.0, v162
	v_add_f32_e32 v163, 1.0, v163
	v_div_scale_f32 v164, s[76:77], v156, v156, 1.0
	v_div_scale_f32 v165, s[76:77], v157, v157, 1.0
	v_div_scale_f32 v166, s[76:77], v158, v158, 1.0
	v_div_scale_f32 v167, s[76:77], v159, v159, 1.0
	v_div_scale_f32 v172, s[76:77], v160, v160, 1.0
	v_div_scale_f32 v173, s[76:77], v161, v161, 1.0
	v_div_scale_f32 v174, s[76:77], v162, v162, 1.0
	v_div_scale_f32 v175, s[76:77], v163, v163, 1.0
	v_rcp_f32_e32 v176, v164
	v_rcp_f32_e32 v177, v165
	v_rcp_f32_e32 v178, v166
	v_rcp_f32_e32 v179, v167
	v_rcp_f32_e32 v180, v172
	v_rcp_f32_e32 v181, v173
	v_rcp_f32_e32 v182, v174
	v_rcp_f32_e32 v183, v175
	v_fma_f32 v148, -v164, v176, 1.0
	v_fma_f32 v149, -v165, v177, 1.0
	v_fma_f32 v150, -v166, v178, 1.0
	v_fma_f32 v151, -v167, v179, 1.0
	v_fma_f32 v152, -v172, v180, 1.0
	v_fma_f32 v153, -v173, v181, 1.0
	v_fma_f32 v154, -v174, v182, 1.0
	v_fma_f32 v155, -v175, v183, 1.0
	v_fmac_f32_e32 v176, v148, v176
	v_fmac_f32_e32 v177, v149, v177
	v_fmac_f32_e32 v178, v150, v178
	v_fmac_f32_e32 v179, v151, v179
	v_fmac_f32_e32 v180, v152, v180
	v_fmac_f32_e32 v181, v153, v181
	v_fmac_f32_e32 v182, v154, v182
	v_fmac_f32_e32 v183, v155, v183
	v_div_scale_f32 v184, vcc, 1.0, v156, 1.0
	v_mul_f32_e32 v192, v184, v176
	v_fma_f32 v148, -v164, v192, v184
	v_fmac_f32_e32 v192, v148, v176
	v_fma_f32 v184, -v164, v192, v184
	v_div_fmas_f32 v184, v184, v176, v192
	v_div_fixup_f32 v148, v184, v156, 1.0
	v_div_scale_f32 v185, vcc, 1.0, v157, 1.0
	v_mul_f32_e32 v193, v185, v177
	v_fma_f32 v149, -v165, v193, v185
	v_fmac_f32_e32 v193, v149, v177
	v_fma_f32 v185, -v165, v193, v185
	v_div_fmas_f32 v185, v185, v177, v193
	v_div_fixup_f32 v149, v185, v157, 1.0
	v_div_scale_f32 v186, vcc, 1.0, v158, 1.0
	v_mul_f32_e32 v194, v186, v178
	v_fma_f32 v150, -v166, v194, v186
	v_fmac_f32_e32 v194, v150, v178
	v_fma_f32 v186, -v166, v194, v186
	v_div_fmas_f32 v186, v186, v178, v194
	v_div_fixup_f32 v150, v186, v158, 1.0
	v_div_scale_f32 v187, vcc, 1.0, v159, 1.0
	v_mul_f32_e32 v195, v187, v179
	v_fma_f32 v151, -v167, v195, v187
	v_fmac_f32_e32 v195, v151, v179
	v_fma_f32 v187, -v167, v195, v187
	v_div_fmas_f32 v187, v187, v179, v195
	v_div_fixup_f32 v151, v187, v159, 1.0
	v_div_scale_f32 v188, vcc, 1.0, v160, 1.0
	v_mul_f32_e32 v196, v188, v180
	v_fma_f32 v152, -v172, v196, v188
	v_fmac_f32_e32 v196, v152, v180
	v_fma_f32 v188, -v172, v196, v188
	v_div_fmas_f32 v188, v188, v180, v196
	v_div_fixup_f32 v152, v188, v160, 1.0
	v_div_scale_f32 v189, vcc, 1.0, v161, 1.0
	v_mul_f32_e32 v197, v189, v181
	v_fma_f32 v153, -v173, v197, v189
	v_fmac_f32_e32 v197, v153, v181
	v_fma_f32 v189, -v173, v197, v189
	v_div_fmas_f32 v189, v189, v181, v197
	v_div_fixup_f32 v153, v189, v161, 1.0
	v_div_scale_f32 v190, vcc, 1.0, v162, 1.0
	v_mul_f32_e32 v198, v190, v182
	v_fma_f32 v154, -v174, v198, v190
	v_fmac_f32_e32 v198, v154, v182
	v_fma_f32 v190, -v174, v198, v190
	v_div_fmas_f32 v190, v190, v182, v198
	v_div_fixup_f32 v154, v190, v162, 1.0
	v_div_scale_f32 v191, vcc, 1.0, v163, 1.0
	v_mul_f32_e32 v199, v191, v183
	v_fma_f32 v155, -v175, v199, v191
	v_fmac_f32_e32 v199, v155, v183
	v_fma_f32 v191, -v175, v199, v191
	v_div_fmas_f32 v191, v191, v183, v199
	v_div_fixup_f32 v155, v191, v163, 1.0
	v_cvt_pk_bf16_f32 v200, v148, v149
	v_cvt_pk_bf16_f32 v201, v150, v151
	v_cvt_pk_bf16_f32 v202, v152, v153
	v_cvt_pk_bf16_f32 v203, v154, v155
	global_store_dwordx4 v243, v[200:203], s[84:85]
	s_add_u32 s84, s84, 0x1000
	s_addc_u32 s85, s85, 0
	v_add_f32_e32 v148, v8, v136
	v_add_f32_e32 v149, v9, v137
	v_add_f32_e32 v150, v10, v138
	v_add_f32_e32 v151, v11, v139
	v_add_f32_e32 v152, v12, v140
	v_add_f32_e32 v153, v13, v141
	v_add_f32_e32 v154, v14, v142
	v_add_f32_e32 v155, v15, v143
	v_mul_f32_e32 v148, 0xbfb8aa3b, v148
	v_mul_f32_e32 v149, 0xbfb8aa3b, v149
	v_mul_f32_e32 v150, 0xbfb8aa3b, v150
	v_mul_f32_e32 v151, 0xbfb8aa3b, v151
	v_mul_f32_e32 v152, 0xbfb8aa3b, v152
	v_mul_f32_e32 v153, 0xbfb8aa3b, v153
	v_mul_f32_e32 v154, 0xbfb8aa3b, v154
	v_mul_f32_e32 v155, 0xbfb8aa3b, v155
	v_exp_f32_e32 v156, v148
	v_exp_f32_e32 v157, v149
	v_exp_f32_e32 v158, v150
	v_exp_f32_e32 v159, v151
	v_exp_f32_e32 v160, v152
	v_exp_f32_e32 v161, v153
	v_exp_f32_e32 v162, v154
	v_exp_f32_e32 v163, v155
	v_add_f32_e32 v156, 1.0, v156
	v_add_f32_e32 v157, 1.0, v157
	v_add_f32_e32 v158, 1.0, v158
	v_add_f32_e32 v159, 1.0, v159
	v_add_f32_e32 v160, 1.0, v160
	v_add_f32_e32 v161, 1.0, v161
	v_add_f32_e32 v162, 1.0, v162
	v_add_f32_e32 v163, 1.0, v163
	v_div_scale_f32 v164, s[76:77], v156, v156, 1.0
	v_div_scale_f32 v165, s[76:77], v157, v157, 1.0
	v_div_scale_f32 v166, s[76:77], v158, v158, 1.0
	v_div_scale_f32 v167, s[76:77], v159, v159, 1.0
	v_div_scale_f32 v172, s[76:77], v160, v160, 1.0
	v_div_scale_f32 v173, s[76:77], v161, v161, 1.0
	v_div_scale_f32 v174, s[76:77], v162, v162, 1.0
	v_div_scale_f32 v175, s[76:77], v163, v163, 1.0
	v_rcp_f32_e32 v176, v164
	v_rcp_f32_e32 v177, v165
	v_rcp_f32_e32 v178, v166
	v_rcp_f32_e32 v179, v167
	v_rcp_f32_e32 v180, v172
	v_rcp_f32_e32 v181, v173
	v_rcp_f32_e32 v182, v174
	v_rcp_f32_e32 v183, v175
	v_fma_f32 v148, -v164, v176, 1.0
	v_fma_f32 v149, -v165, v177, 1.0
	v_fma_f32 v150, -v166, v178, 1.0
	v_fma_f32 v151, -v167, v179, 1.0
	v_fma_f32 v152, -v172, v180, 1.0
	v_fma_f32 v153, -v173, v181, 1.0
	v_fma_f32 v154, -v174, v182, 1.0
	v_fma_f32 v155, -v175, v183, 1.0
	v_fmac_f32_e32 v176, v148, v176
	v_fmac_f32_e32 v177, v149, v177
	v_fmac_f32_e32 v178, v150, v178
	v_fmac_f32_e32 v179, v151, v179
	v_fmac_f32_e32 v180, v152, v180
	v_fmac_f32_e32 v181, v153, v181
	v_fmac_f32_e32 v182, v154, v182
	v_fmac_f32_e32 v183, v155, v183
	v_div_scale_f32 v184, vcc, 1.0, v156, 1.0
	v_mul_f32_e32 v192, v184, v176
	v_fma_f32 v148, -v164, v192, v184
	v_fmac_f32_e32 v192, v148, v176
	v_fma_f32 v184, -v164, v192, v184
	v_div_fmas_f32 v184, v184, v176, v192
	v_div_fixup_f32 v148, v184, v156, 1.0
	v_div_scale_f32 v185, vcc, 1.0, v157, 1.0
	v_mul_f32_e32 v193, v185, v177
	v_fma_f32 v149, -v165, v193, v185
	v_fmac_f32_e32 v193, v149, v177
	v_fma_f32 v185, -v165, v193, v185
	v_div_fmas_f32 v185, v185, v177, v193
	v_div_fixup_f32 v149, v185, v157, 1.0
	v_div_scale_f32 v186, vcc, 1.0, v158, 1.0
	v_mul_f32_e32 v194, v186, v178
	v_fma_f32 v150, -v166, v194, v186
	v_fmac_f32_e32 v194, v150, v178
	v_fma_f32 v186, -v166, v194, v186
	v_div_fmas_f32 v186, v186, v178, v194
	v_div_fixup_f32 v150, v186, v158, 1.0
	v_div_scale_f32 v187, vcc, 1.0, v159, 1.0
	v_mul_f32_e32 v195, v187, v179
	v_fma_f32 v151, -v167, v195, v187
	v_fmac_f32_e32 v195, v151, v179
	v_fma_f32 v187, -v167, v195, v187
	v_div_fmas_f32 v187, v187, v179, v195
	v_div_fixup_f32 v151, v187, v159, 1.0
	v_div_scale_f32 v188, vcc, 1.0, v160, 1.0
	v_mul_f32_e32 v196, v188, v180
	v_fma_f32 v152, -v172, v196, v188
	v_fmac_f32_e32 v196, v152, v180
	v_fma_f32 v188, -v172, v196, v188
	v_div_fmas_f32 v188, v188, v180, v196
	v_div_fixup_f32 v152, v188, v160, 1.0
	v_div_scale_f32 v189, vcc, 1.0, v161, 1.0
	v_mul_f32_e32 v197, v189, v181
	v_fma_f32 v153, -v173, v197, v189
	v_fmac_f32_e32 v197, v153, v181
	v_fma_f32 v189, -v173, v197, v189
	v_div_fmas_f32 v189, v189, v181, v197
	v_div_fixup_f32 v153, v189, v161, 1.0
	v_div_scale_f32 v190, vcc, 1.0, v162, 1.0
	v_mul_f32_e32 v198, v190, v182
	v_fma_f32 v154, -v174, v198, v190
	v_fmac_f32_e32 v198, v154, v182
	v_fma_f32 v190, -v174, v198, v190
	v_div_fmas_f32 v190, v190, v182, v198
	v_div_fixup_f32 v154, v190, v162, 1.0
	v_div_scale_f32 v191, vcc, 1.0, v163, 1.0
	v_mul_f32_e32 v199, v191, v183
	v_fma_f32 v155, -v175, v199, v191
	v_fmac_f32_e32 v199, v155, v183
	v_fma_f32 v191, -v175, v199, v191
	v_div_fmas_f32 v191, v191, v183, v199
	v_div_fixup_f32 v155, v191, v163, 1.0
	v_cvt_pk_bf16_f32 v204, v148, v149
	v_cvt_pk_bf16_f32 v205, v150, v151
	v_cvt_pk_bf16_f32 v206, v152, v153
	v_cvt_pk_bf16_f32 v207, v154, v155
	global_store_dwordx4 v243, v[204:207], s[84:85]
	s_add_u32 s84, s84, 0x1000
	s_addc_u32 s85, s85, 0
	v_add_f32_e32 v148, v16, v128
	v_add_f32_e32 v149, v17, v129
	v_add_f32_e32 v150, v18, v130
	v_add_f32_e32 v151, v19, v131
	v_add_f32_e32 v152, v20, v132
	v_add_f32_e32 v153, v21, v133
	v_add_f32_e32 v154, v22, v134
	v_add_f32_e32 v155, v23, v135
	v_mul_f32_e32 v148, 0xbfb8aa3b, v148
	v_mul_f32_e32 v149, 0xbfb8aa3b, v149
	v_mul_f32_e32 v150, 0xbfb8aa3b, v150
	v_mul_f32_e32 v151, 0xbfb8aa3b, v151
	v_mul_f32_e32 v152, 0xbfb8aa3b, v152
	v_mul_f32_e32 v153, 0xbfb8aa3b, v153
	v_mul_f32_e32 v154, 0xbfb8aa3b, v154
	v_mul_f32_e32 v155, 0xbfb8aa3b, v155
	v_exp_f32_e32 v156, v148
	v_exp_f32_e32 v157, v149
	v_exp_f32_e32 v158, v150
	v_exp_f32_e32 v159, v151
	v_exp_f32_e32 v160, v152
	v_exp_f32_e32 v161, v153
	v_exp_f32_e32 v162, v154
	v_exp_f32_e32 v163, v155
	v_add_f32_e32 v156, 1.0, v156
	v_add_f32_e32 v157, 1.0, v157
	v_add_f32_e32 v158, 1.0, v158
	v_add_f32_e32 v159, 1.0, v159
	v_add_f32_e32 v160, 1.0, v160
	v_add_f32_e32 v161, 1.0, v161
	v_add_f32_e32 v162, 1.0, v162
	v_add_f32_e32 v163, 1.0, v163
	v_div_scale_f32 v164, s[76:77], v156, v156, 1.0
	v_div_scale_f32 v165, s[76:77], v157, v157, 1.0
	v_div_scale_f32 v166, s[76:77], v158, v158, 1.0
	v_div_scale_f32 v167, s[76:77], v159, v159, 1.0
	v_div_scale_f32 v172, s[76:77], v160, v160, 1.0
	v_div_scale_f32 v173, s[76:77], v161, v161, 1.0
	v_div_scale_f32 v174, s[76:77], v162, v162, 1.0
	v_div_scale_f32 v175, s[76:77], v163, v163, 1.0
	v_rcp_f32_e32 v176, v164
	v_rcp_f32_e32 v177, v165
	v_rcp_f32_e32 v178, v166
	v_rcp_f32_e32 v179, v167
	v_rcp_f32_e32 v180, v172
	v_rcp_f32_e32 v181, v173
	v_rcp_f32_e32 v182, v174
	v_rcp_f32_e32 v183, v175
	v_fma_f32 v148, -v164, v176, 1.0
	v_fma_f32 v149, -v165, v177, 1.0
	v_fma_f32 v150, -v166, v178, 1.0
	v_fma_f32 v151, -v167, v179, 1.0
	v_fma_f32 v152, -v172, v180, 1.0
	v_fma_f32 v153, -v173, v181, 1.0
	v_fma_f32 v154, -v174, v182, 1.0
	v_fma_f32 v155, -v175, v183, 1.0
	v_fmac_f32_e32 v176, v148, v176
	v_fmac_f32_e32 v177, v149, v177
	v_fmac_f32_e32 v178, v150, v178
	v_fmac_f32_e32 v179, v151, v179
	v_fmac_f32_e32 v180, v152, v180
	v_fmac_f32_e32 v181, v153, v181
	v_fmac_f32_e32 v182, v154, v182
	v_fmac_f32_e32 v183, v155, v183
	v_div_scale_f32 v184, vcc, 1.0, v156, 1.0
	v_mul_f32_e32 v192, v184, v176
	v_fma_f32 v148, -v164, v192, v184
	v_fmac_f32_e32 v192, v148, v176
	v_fma_f32 v184, -v164, v192, v184
	v_div_fmas_f32 v184, v184, v176, v192
	v_div_fixup_f32 v148, v184, v156, 1.0
	v_div_scale_f32 v185, vcc, 1.0, v157, 1.0
	v_mul_f32_e32 v193, v185, v177
	v_fma_f32 v149, -v165, v193, v185
	v_fmac_f32_e32 v193, v149, v177
	v_fma_f32 v185, -v165, v193, v185
	v_div_fmas_f32 v185, v185, v177, v193
	v_div_fixup_f32 v149, v185, v157, 1.0
	v_div_scale_f32 v186, vcc, 1.0, v158, 1.0
	v_mul_f32_e32 v194, v186, v178
	v_fma_f32 v150, -v166, v194, v186
	v_fmac_f32_e32 v194, v150, v178
	v_fma_f32 v186, -v166, v194, v186
	v_div_fmas_f32 v186, v186, v178, v194
	v_div_fixup_f32 v150, v186, v158, 1.0
	v_div_scale_f32 v187, vcc, 1.0, v159, 1.0
	v_mul_f32_e32 v195, v187, v179
	v_fma_f32 v151, -v167, v195, v187
	v_fmac_f32_e32 v195, v151, v179
	v_fma_f32 v187, -v167, v195, v187
	v_div_fmas_f32 v187, v187, v179, v195
	v_div_fixup_f32 v151, v187, v159, 1.0
	v_div_scale_f32 v188, vcc, 1.0, v160, 1.0
	v_mul_f32_e32 v196, v188, v180
	v_fma_f32 v152, -v172, v196, v188
	v_fmac_f32_e32 v196, v152, v180
	v_fma_f32 v188, -v172, v196, v188
	v_div_fmas_f32 v188, v188, v180, v196
	v_div_fixup_f32 v152, v188, v160, 1.0
	v_div_scale_f32 v189, vcc, 1.0, v161, 1.0
	v_mul_f32_e32 v197, v189, v181
	v_fma_f32 v153, -v173, v197, v189
	v_fmac_f32_e32 v197, v153, v181
	v_fma_f32 v189, -v173, v197, v189
	v_div_fmas_f32 v189, v189, v181, v197
	v_div_fixup_f32 v153, v189, v161, 1.0
	v_div_scale_f32 v190, vcc, 1.0, v162, 1.0
	v_mul_f32_e32 v198, v190, v182
	v_fma_f32 v154, -v174, v198, v190
	v_fmac_f32_e32 v198, v154, v182
	v_fma_f32 v190, -v174, v198, v190
	v_div_fmas_f32 v190, v190, v182, v198
	v_div_fixup_f32 v154, v190, v162, 1.0
	v_div_scale_f32 v191, vcc, 1.0, v163, 1.0
	v_mul_f32_e32 v199, v191, v183
	v_fma_f32 v155, -v175, v199, v191
	v_fmac_f32_e32 v199, v155, v183
	v_fma_f32 v191, -v175, v199, v191
	v_div_fmas_f32 v191, v191, v183, v199
	v_div_fixup_f32 v155, v191, v163, 1.0
	v_cvt_pk_bf16_f32 v200, v148, v149
	v_cvt_pk_bf16_f32 v201, v150, v151
	v_cvt_pk_bf16_f32 v202, v152, v153
	v_cvt_pk_bf16_f32 v203, v154, v155
	global_store_dwordx4 v243, v[200:203], s[84:85]
	s_add_u32 s84, s84, 0x1000
	s_addc_u32 s85, s85, 0
	v_add_f32_e32 v148, v24, v136
	v_add_f32_e32 v149, v25, v137
	v_add_f32_e32 v150, v26, v138
	v_add_f32_e32 v151, v27, v139
	v_add_f32_e32 v152, v28, v140
	v_add_f32_e32 v153, v29, v141
	v_add_f32_e32 v154, v30, v142
	v_add_f32_e32 v155, v31, v143
	v_mul_f32_e32 v148, 0xbfb8aa3b, v148
	v_mul_f32_e32 v149, 0xbfb8aa3b, v149
	v_mul_f32_e32 v150, 0xbfb8aa3b, v150
	v_mul_f32_e32 v151, 0xbfb8aa3b, v151
	v_mul_f32_e32 v152, 0xbfb8aa3b, v152
	v_mul_f32_e32 v153, 0xbfb8aa3b, v153
	v_mul_f32_e32 v154, 0xbfb8aa3b, v154
	v_mul_f32_e32 v155, 0xbfb8aa3b, v155
	v_exp_f32_e32 v156, v148
	v_exp_f32_e32 v157, v149
	v_exp_f32_e32 v158, v150
	v_exp_f32_e32 v159, v151
	v_exp_f32_e32 v160, v152
	v_exp_f32_e32 v161, v153
	v_exp_f32_e32 v162, v154
	v_exp_f32_e32 v163, v155
	v_add_f32_e32 v156, 1.0, v156
	v_add_f32_e32 v157, 1.0, v157
	v_add_f32_e32 v158, 1.0, v158
	v_add_f32_e32 v159, 1.0, v159
	v_add_f32_e32 v160, 1.0, v160
	v_add_f32_e32 v161, 1.0, v161
	v_add_f32_e32 v162, 1.0, v162
	v_add_f32_e32 v163, 1.0, v163
	v_div_scale_f32 v164, s[76:77], v156, v156, 1.0
	v_div_scale_f32 v165, s[76:77], v157, v157, 1.0
	v_div_scale_f32 v166, s[76:77], v158, v158, 1.0
	v_div_scale_f32 v167, s[76:77], v159, v159, 1.0
	v_div_scale_f32 v172, s[76:77], v160, v160, 1.0
	v_div_scale_f32 v173, s[76:77], v161, v161, 1.0
	v_div_scale_f32 v174, s[76:77], v162, v162, 1.0
	v_div_scale_f32 v175, s[76:77], v163, v163, 1.0
	v_rcp_f32_e32 v176, v164
	v_rcp_f32_e32 v177, v165
	v_rcp_f32_e32 v178, v166
	v_rcp_f32_e32 v179, v167
	v_rcp_f32_e32 v180, v172
	v_rcp_f32_e32 v181, v173
	v_rcp_f32_e32 v182, v174
	v_rcp_f32_e32 v183, v175
	v_fma_f32 v148, -v164, v176, 1.0
	v_fma_f32 v149, -v165, v177, 1.0
	v_fma_f32 v150, -v166, v178, 1.0
	v_fma_f32 v151, -v167, v179, 1.0
	v_fma_f32 v152, -v172, v180, 1.0
	v_fma_f32 v153, -v173, v181, 1.0
	v_fma_f32 v154, -v174, v182, 1.0
	v_fma_f32 v155, -v175, v183, 1.0
	v_fmac_f32_e32 v176, v148, v176
	v_fmac_f32_e32 v177, v149, v177
	v_fmac_f32_e32 v178, v150, v178
	v_fmac_f32_e32 v179, v151, v179
	v_fmac_f32_e32 v180, v152, v180
	v_fmac_f32_e32 v181, v153, v181
	v_fmac_f32_e32 v182, v154, v182
	v_fmac_f32_e32 v183, v155, v183
	v_div_scale_f32 v184, vcc, 1.0, v156, 1.0
	v_mul_f32_e32 v192, v184, v176
	v_fma_f32 v148, -v164, v192, v184
	v_fmac_f32_e32 v192, v148, v176
	v_fma_f32 v184, -v164, v192, v184
	v_div_fmas_f32 v184, v184, v176, v192
	v_div_fixup_f32 v148, v184, v156, 1.0
	v_div_scale_f32 v185, vcc, 1.0, v157, 1.0
	v_mul_f32_e32 v193, v185, v177
	v_fma_f32 v149, -v165, v193, v185
	v_fmac_f32_e32 v193, v149, v177
	v_fma_f32 v185, -v165, v193, v185
	v_div_fmas_f32 v185, v185, v177, v193
	v_div_fixup_f32 v149, v185, v157, 1.0
	v_div_scale_f32 v186, vcc, 1.0, v158, 1.0
	v_mul_f32_e32 v194, v186, v178
	v_fma_f32 v150, -v166, v194, v186
	v_fmac_f32_e32 v194, v150, v178
	v_fma_f32 v186, -v166, v194, v186
	v_div_fmas_f32 v186, v186, v178, v194
	v_div_fixup_f32 v150, v186, v158, 1.0
	v_div_scale_f32 v187, vcc, 1.0, v159, 1.0
	v_mul_f32_e32 v195, v187, v179
	v_fma_f32 v151, -v167, v195, v187
	v_fmac_f32_e32 v195, v151, v179
	v_fma_f32 v187, -v167, v195, v187
	v_div_fmas_f32 v187, v187, v179, v195
	v_div_fixup_f32 v151, v187, v159, 1.0
	v_div_scale_f32 v188, vcc, 1.0, v160, 1.0
	v_mul_f32_e32 v196, v188, v180
	v_fma_f32 v152, -v172, v196, v188
	v_fmac_f32_e32 v196, v152, v180
	v_fma_f32 v188, -v172, v196, v188
	v_div_fmas_f32 v188, v188, v180, v196
	v_div_fixup_f32 v152, v188, v160, 1.0
	v_div_scale_f32 v189, vcc, 1.0, v161, 1.0
	v_mul_f32_e32 v197, v189, v181
	v_fma_f32 v153, -v173, v197, v189
	v_fmac_f32_e32 v197, v153, v181
	v_fma_f32 v189, -v173, v197, v189
	v_div_fmas_f32 v189, v189, v181, v197
	v_div_fixup_f32 v153, v189, v161, 1.0
	v_div_scale_f32 v190, vcc, 1.0, v162, 1.0
	v_mul_f32_e32 v198, v190, v182
	v_fma_f32 v154, -v174, v198, v190
	v_fmac_f32_e32 v198, v154, v182
	v_fma_f32 v190, -v174, v198, v190
	v_div_fmas_f32 v190, v190, v182, v198
	v_div_fixup_f32 v154, v190, v162, 1.0
	v_div_scale_f32 v191, vcc, 1.0, v163, 1.0
	v_mul_f32_e32 v199, v191, v183
	v_fma_f32 v155, -v175, v199, v191
	v_fmac_f32_e32 v199, v155, v183
	v_fma_f32 v191, -v175, v199, v191
	v_div_fmas_f32 v191, v191, v183, v199
	v_div_fixup_f32 v155, v191, v163, 1.0
	v_cvt_pk_bf16_f32 v204, v148, v149
	v_cvt_pk_bf16_f32 v205, v150, v151
	v_cvt_pk_bf16_f32 v206, v152, v153
	v_cvt_pk_bf16_f32 v207, v154, v155
	global_store_dwordx4 v243, v[204:207], s[84:85]
	s_add_u32 s84, s84, 0x1000
	s_addc_u32 s85, s85, 0
	v_add_f32_e32 v148, v32, v128
	v_add_f32_e32 v149, v33, v129
	v_add_f32_e32 v150, v34, v130
	v_add_f32_e32 v151, v35, v131
	v_add_f32_e32 v152, v36, v132
	v_add_f32_e32 v153, v37, v133
	v_add_f32_e32 v154, v38, v134
	v_add_f32_e32 v155, v39, v135
	v_mul_f32_e32 v148, 0xbfb8aa3b, v148
	v_mul_f32_e32 v149, 0xbfb8aa3b, v149
	v_mul_f32_e32 v150, 0xbfb8aa3b, v150
	v_mul_f32_e32 v151, 0xbfb8aa3b, v151
	v_mul_f32_e32 v152, 0xbfb8aa3b, v152
	v_mul_f32_e32 v153, 0xbfb8aa3b, v153
	v_mul_f32_e32 v154, 0xbfb8aa3b, v154
	v_mul_f32_e32 v155, 0xbfb8aa3b, v155
	v_exp_f32_e32 v156, v148
	v_exp_f32_e32 v157, v149
	v_exp_f32_e32 v158, v150
	v_exp_f32_e32 v159, v151
	v_exp_f32_e32 v160, v152
	v_exp_f32_e32 v161, v153
	v_exp_f32_e32 v162, v154
	v_exp_f32_e32 v163, v155
	v_add_f32_e32 v156, 1.0, v156
	v_add_f32_e32 v157, 1.0, v157
	v_add_f32_e32 v158, 1.0, v158
	v_add_f32_e32 v159, 1.0, v159
	v_add_f32_e32 v160, 1.0, v160
	v_add_f32_e32 v161, 1.0, v161
	v_add_f32_e32 v162, 1.0, v162
	v_add_f32_e32 v163, 1.0, v163
	v_div_scale_f32 v164, s[76:77], v156, v156, 1.0
	v_div_scale_f32 v165, s[76:77], v157, v157, 1.0
	v_div_scale_f32 v166, s[76:77], v158, v158, 1.0
	v_div_scale_f32 v167, s[76:77], v159, v159, 1.0
	v_div_scale_f32 v172, s[76:77], v160, v160, 1.0
	v_div_scale_f32 v173, s[76:77], v161, v161, 1.0
	v_div_scale_f32 v174, s[76:77], v162, v162, 1.0
	v_div_scale_f32 v175, s[76:77], v163, v163, 1.0
	v_rcp_f32_e32 v176, v164
	v_rcp_f32_e32 v177, v165
	v_rcp_f32_e32 v178, v166
	v_rcp_f32_e32 v179, v167
	v_rcp_f32_e32 v180, v172
	v_rcp_f32_e32 v181, v173
	v_rcp_f32_e32 v182, v174
	v_rcp_f32_e32 v183, v175
	v_fma_f32 v148, -v164, v176, 1.0
	v_fma_f32 v149, -v165, v177, 1.0
	v_fma_f32 v150, -v166, v178, 1.0
	v_fma_f32 v151, -v167, v179, 1.0
	v_fma_f32 v152, -v172, v180, 1.0
	v_fma_f32 v153, -v173, v181, 1.0
	v_fma_f32 v154, -v174, v182, 1.0
	v_fma_f32 v155, -v175, v183, 1.0
	v_fmac_f32_e32 v176, v148, v176
	v_fmac_f32_e32 v177, v149, v177
	v_fmac_f32_e32 v178, v150, v178
	v_fmac_f32_e32 v179, v151, v179
	v_fmac_f32_e32 v180, v152, v180
	v_fmac_f32_e32 v181, v153, v181
	v_fmac_f32_e32 v182, v154, v182
	v_fmac_f32_e32 v183, v155, v183
	v_div_scale_f32 v184, vcc, 1.0, v156, 1.0
	v_mul_f32_e32 v192, v184, v176
	v_fma_f32 v148, -v164, v192, v184
	v_fmac_f32_e32 v192, v148, v176
	v_fma_f32 v184, -v164, v192, v184
	v_div_fmas_f32 v184, v184, v176, v192
	v_div_fixup_f32 v148, v184, v156, 1.0
	v_div_scale_f32 v185, vcc, 1.0, v157, 1.0
	v_mul_f32_e32 v193, v185, v177
	v_fma_f32 v149, -v165, v193, v185
	v_fmac_f32_e32 v193, v149, v177
	v_fma_f32 v185, -v165, v193, v185
	v_div_fmas_f32 v185, v185, v177, v193
	v_div_fixup_f32 v149, v185, v157, 1.0
	v_div_scale_f32 v186, vcc, 1.0, v158, 1.0
	v_mul_f32_e32 v194, v186, v178
	v_fma_f32 v150, -v166, v194, v186
	v_fmac_f32_e32 v194, v150, v178
	v_fma_f32 v186, -v166, v194, v186
	v_div_fmas_f32 v186, v186, v178, v194
	v_div_fixup_f32 v150, v186, v158, 1.0
	v_div_scale_f32 v187, vcc, 1.0, v159, 1.0
	v_mul_f32_e32 v195, v187, v179
	v_fma_f32 v151, -v167, v195, v187
	v_fmac_f32_e32 v195, v151, v179
	v_fma_f32 v187, -v167, v195, v187
	v_div_fmas_f32 v187, v187, v179, v195
	v_div_fixup_f32 v151, v187, v159, 1.0
	v_div_scale_f32 v188, vcc, 1.0, v160, 1.0
	v_mul_f32_e32 v196, v188, v180
	v_fma_f32 v152, -v172, v196, v188
	v_fmac_f32_e32 v196, v152, v180
	v_fma_f32 v188, -v172, v196, v188
	v_div_fmas_f32 v188, v188, v180, v196
	v_div_fixup_f32 v152, v188, v160, 1.0
	v_div_scale_f32 v189, vcc, 1.0, v161, 1.0
	v_mul_f32_e32 v197, v189, v181
	v_fma_f32 v153, -v173, v197, v189
	v_fmac_f32_e32 v197, v153, v181
	v_fma_f32 v189, -v173, v197, v189
	v_div_fmas_f32 v189, v189, v181, v197
	v_div_fixup_f32 v153, v189, v161, 1.0
	v_div_scale_f32 v190, vcc, 1.0, v162, 1.0
	v_mul_f32_e32 v198, v190, v182
	v_fma_f32 v154, -v174, v198, v190
	v_fmac_f32_e32 v198, v154, v182
	v_fma_f32 v190, -v174, v198, v190
	v_div_fmas_f32 v190, v190, v182, v198
	v_div_fixup_f32 v154, v190, v162, 1.0
	v_div_scale_f32 v191, vcc, 1.0, v163, 1.0
	v_mul_f32_e32 v199, v191, v183
	v_fma_f32 v155, -v175, v199, v191
	v_fmac_f32_e32 v199, v155, v183
	v_fma_f32 v191, -v175, v199, v191
	v_div_fmas_f32 v191, v191, v183, v199
	v_div_fixup_f32 v155, v191, v163, 1.0
	v_cvt_pk_bf16_f32 v200, v148, v149
	v_cvt_pk_bf16_f32 v201, v150, v151
	v_cvt_pk_bf16_f32 v202, v152, v153
	v_cvt_pk_bf16_f32 v203, v154, v155
	global_store_dwordx4 v243, v[200:203], s[84:85]
	s_add_u32 s84, s84, 0x1000
	s_addc_u32 s85, s85, 0
	v_add_f32_e32 v148, v40, v136
	v_add_f32_e32 v149, v41, v137
	v_add_f32_e32 v150, v42, v138
	v_add_f32_e32 v151, v43, v139
	v_add_f32_e32 v152, v44, v140
	v_add_f32_e32 v153, v45, v141
	v_add_f32_e32 v154, v46, v142
	v_add_f32_e32 v155, v47, v143
	v_mul_f32_e32 v148, 0xbfb8aa3b, v148
	v_mul_f32_e32 v149, 0xbfb8aa3b, v149
	v_mul_f32_e32 v150, 0xbfb8aa3b, v150
	v_mul_f32_e32 v151, 0xbfb8aa3b, v151
	v_mul_f32_e32 v152, 0xbfb8aa3b, v152
	v_mul_f32_e32 v153, 0xbfb8aa3b, v153
	v_mul_f32_e32 v154, 0xbfb8aa3b, v154
	v_mul_f32_e32 v155, 0xbfb8aa3b, v155
	v_exp_f32_e32 v156, v148
	v_exp_f32_e32 v157, v149
	v_exp_f32_e32 v158, v150
	v_exp_f32_e32 v159, v151
	v_exp_f32_e32 v160, v152
	v_exp_f32_e32 v161, v153
	v_exp_f32_e32 v162, v154
	v_exp_f32_e32 v163, v155
	v_add_f32_e32 v156, 1.0, v156
	v_add_f32_e32 v157, 1.0, v157
	v_add_f32_e32 v158, 1.0, v158
	v_add_f32_e32 v159, 1.0, v159
	v_add_f32_e32 v160, 1.0, v160
	v_add_f32_e32 v161, 1.0, v161
	v_add_f32_e32 v162, 1.0, v162
	v_add_f32_e32 v163, 1.0, v163
	v_div_scale_f32 v164, s[76:77], v156, v156, 1.0
	v_div_scale_f32 v165, s[76:77], v157, v157, 1.0
	v_div_scale_f32 v166, s[76:77], v158, v158, 1.0
	v_div_scale_f32 v167, s[76:77], v159, v159, 1.0
	v_div_scale_f32 v172, s[76:77], v160, v160, 1.0
	v_div_scale_f32 v173, s[76:77], v161, v161, 1.0
	v_div_scale_f32 v174, s[76:77], v162, v162, 1.0
	v_div_scale_f32 v175, s[76:77], v163, v163, 1.0
	v_rcp_f32_e32 v176, v164
	v_rcp_f32_e32 v177, v165
	v_rcp_f32_e32 v178, v166
	v_rcp_f32_e32 v179, v167
	v_rcp_f32_e32 v180, v172
	v_rcp_f32_e32 v181, v173
	v_rcp_f32_e32 v182, v174
	v_rcp_f32_e32 v183, v175
	v_fma_f32 v148, -v164, v176, 1.0
	v_fma_f32 v149, -v165, v177, 1.0
	v_fma_f32 v150, -v166, v178, 1.0
	v_fma_f32 v151, -v167, v179, 1.0
	v_fma_f32 v152, -v172, v180, 1.0
	v_fma_f32 v153, -v173, v181, 1.0
	v_fma_f32 v154, -v174, v182, 1.0
	v_fma_f32 v155, -v175, v183, 1.0
	v_fmac_f32_e32 v176, v148, v176
	v_fmac_f32_e32 v177, v149, v177
	v_fmac_f32_e32 v178, v150, v178
	v_fmac_f32_e32 v179, v151, v179
	v_fmac_f32_e32 v180, v152, v180
	v_fmac_f32_e32 v181, v153, v181
	v_fmac_f32_e32 v182, v154, v182
	v_fmac_f32_e32 v183, v155, v183
	v_div_scale_f32 v184, vcc, 1.0, v156, 1.0
	v_mul_f32_e32 v192, v184, v176
	v_fma_f32 v148, -v164, v192, v184
	v_fmac_f32_e32 v192, v148, v176
	v_fma_f32 v184, -v164, v192, v184
	v_div_fmas_f32 v184, v184, v176, v192
	v_div_fixup_f32 v148, v184, v156, 1.0
	v_div_scale_f32 v185, vcc, 1.0, v157, 1.0
	v_mul_f32_e32 v193, v185, v177
	v_fma_f32 v149, -v165, v193, v185
	v_fmac_f32_e32 v193, v149, v177
	v_fma_f32 v185, -v165, v193, v185
	v_div_fmas_f32 v185, v185, v177, v193
	v_div_fixup_f32 v149, v185, v157, 1.0
	v_div_scale_f32 v186, vcc, 1.0, v158, 1.0
	v_mul_f32_e32 v194, v186, v178
	v_fma_f32 v150, -v166, v194, v186
	v_fmac_f32_e32 v194, v150, v178
	v_fma_f32 v186, -v166, v194, v186
	v_div_fmas_f32 v186, v186, v178, v194
	v_div_fixup_f32 v150, v186, v158, 1.0
	v_div_scale_f32 v187, vcc, 1.0, v159, 1.0
	v_mul_f32_e32 v195, v187, v179
	v_fma_f32 v151, -v167, v195, v187
	v_fmac_f32_e32 v195, v151, v179
	v_fma_f32 v187, -v167, v195, v187
	v_div_fmas_f32 v187, v187, v179, v195
	v_div_fixup_f32 v151, v187, v159, 1.0
	v_div_scale_f32 v188, vcc, 1.0, v160, 1.0
	v_mul_f32_e32 v196, v188, v180
	v_fma_f32 v152, -v172, v196, v188
	v_fmac_f32_e32 v196, v152, v180
	v_fma_f32 v188, -v172, v196, v188
	v_div_fmas_f32 v188, v188, v180, v196
	v_div_fixup_f32 v152, v188, v160, 1.0
	v_div_scale_f32 v189, vcc, 1.0, v161, 1.0
	v_mul_f32_e32 v197, v189, v181
	v_fma_f32 v153, -v173, v197, v189
	v_fmac_f32_e32 v197, v153, v181
	v_fma_f32 v189, -v173, v197, v189
	v_div_fmas_f32 v189, v189, v181, v197
	v_div_fixup_f32 v153, v189, v161, 1.0
	v_div_scale_f32 v190, vcc, 1.0, v162, 1.0
	v_mul_f32_e32 v198, v190, v182
	v_fma_f32 v154, -v174, v198, v190
	v_fmac_f32_e32 v198, v154, v182
	v_fma_f32 v190, -v174, v198, v190
	v_div_fmas_f32 v190, v190, v182, v198
	v_div_fixup_f32 v154, v190, v162, 1.0
	v_div_scale_f32 v191, vcc, 1.0, v163, 1.0
	v_mul_f32_e32 v199, v191, v183
	v_fma_f32 v155, -v175, v199, v191
	v_fmac_f32_e32 v199, v155, v183
	v_fma_f32 v191, -v175, v199, v191
	v_div_fmas_f32 v191, v191, v183, v199
	v_div_fixup_f32 v155, v191, v163, 1.0
	v_cvt_pk_bf16_f32 v204, v148, v149
	v_cvt_pk_bf16_f32 v205, v150, v151
	v_cvt_pk_bf16_f32 v206, v152, v153
	v_cvt_pk_bf16_f32 v207, v154, v155
	global_store_dwordx4 v243, v[204:207], s[84:85]
	s_add_u32 s84, s84, 0x1000
	s_addc_u32 s85, s85, 0
	v_add_f32_e32 v148, v48, v128
	v_add_f32_e32 v149, v49, v129
	v_add_f32_e32 v150, v50, v130
	v_add_f32_e32 v151, v51, v131
	v_add_f32_e32 v152, v52, v132
	v_add_f32_e32 v153, v53, v133
	v_add_f32_e32 v154, v54, v134
	v_add_f32_e32 v155, v55, v135
	v_mul_f32_e32 v148, 0xbfb8aa3b, v148
	v_mul_f32_e32 v149, 0xbfb8aa3b, v149
	v_mul_f32_e32 v150, 0xbfb8aa3b, v150
	v_mul_f32_e32 v151, 0xbfb8aa3b, v151
	v_mul_f32_e32 v152, 0xbfb8aa3b, v152
	v_mul_f32_e32 v153, 0xbfb8aa3b, v153
	v_mul_f32_e32 v154, 0xbfb8aa3b, v154
	v_mul_f32_e32 v155, 0xbfb8aa3b, v155
	v_exp_f32_e32 v156, v148
	v_exp_f32_e32 v157, v149
	v_exp_f32_e32 v158, v150
	v_exp_f32_e32 v159, v151
	v_exp_f32_e32 v160, v152
	v_exp_f32_e32 v161, v153
	v_exp_f32_e32 v162, v154
	v_exp_f32_e32 v163, v155
	v_add_f32_e32 v156, 1.0, v156
	v_add_f32_e32 v157, 1.0, v157
	v_add_f32_e32 v158, 1.0, v158
	v_add_f32_e32 v159, 1.0, v159
	v_add_f32_e32 v160, 1.0, v160
	v_add_f32_e32 v161, 1.0, v161
	v_add_f32_e32 v162, 1.0, v162
	v_add_f32_e32 v163, 1.0, v163
	v_div_scale_f32 v164, s[76:77], v156, v156, 1.0
	v_div_scale_f32 v165, s[76:77], v157, v157, 1.0
	v_div_scale_f32 v166, s[76:77], v158, v158, 1.0
	v_div_scale_f32 v167, s[76:77], v159, v159, 1.0
	v_div_scale_f32 v172, s[76:77], v160, v160, 1.0
	v_div_scale_f32 v173, s[76:77], v161, v161, 1.0
	v_div_scale_f32 v174, s[76:77], v162, v162, 1.0
	v_div_scale_f32 v175, s[76:77], v163, v163, 1.0
	v_rcp_f32_e32 v176, v164
	v_rcp_f32_e32 v177, v165
	v_rcp_f32_e32 v178, v166
	v_rcp_f32_e32 v179, v167
	v_rcp_f32_e32 v180, v172
	v_rcp_f32_e32 v181, v173
	v_rcp_f32_e32 v182, v174
	v_rcp_f32_e32 v183, v175
	v_fma_f32 v148, -v164, v176, 1.0
	v_fma_f32 v149, -v165, v177, 1.0
	v_fma_f32 v150, -v166, v178, 1.0
	v_fma_f32 v151, -v167, v179, 1.0
	v_fma_f32 v152, -v172, v180, 1.0
	v_fma_f32 v153, -v173, v181, 1.0
	v_fma_f32 v154, -v174, v182, 1.0
	v_fma_f32 v155, -v175, v183, 1.0
	v_fmac_f32_e32 v176, v148, v176
	v_fmac_f32_e32 v177, v149, v177
	v_fmac_f32_e32 v178, v150, v178
	v_fmac_f32_e32 v179, v151, v179
	v_fmac_f32_e32 v180, v152, v180
	v_fmac_f32_e32 v181, v153, v181
	v_fmac_f32_e32 v182, v154, v182
	v_fmac_f32_e32 v183, v155, v183
	v_div_scale_f32 v184, vcc, 1.0, v156, 1.0
	v_mul_f32_e32 v192, v184, v176
	v_fma_f32 v148, -v164, v192, v184
	v_fmac_f32_e32 v192, v148, v176
	v_fma_f32 v184, -v164, v192, v184
	v_div_fmas_f32 v184, v184, v176, v192
	v_div_fixup_f32 v148, v184, v156, 1.0
	v_div_scale_f32 v185, vcc, 1.0, v157, 1.0
	v_mul_f32_e32 v193, v185, v177
	v_fma_f32 v149, -v165, v193, v185
	v_fmac_f32_e32 v193, v149, v177
	v_fma_f32 v185, -v165, v193, v185
	v_div_fmas_f32 v185, v185, v177, v193
	v_div_fixup_f32 v149, v185, v157, 1.0
	v_div_scale_f32 v186, vcc, 1.0, v158, 1.0
	v_mul_f32_e32 v194, v186, v178
	v_fma_f32 v150, -v166, v194, v186
	v_fmac_f32_e32 v194, v150, v178
	v_fma_f32 v186, -v166, v194, v186
	v_div_fmas_f32 v186, v186, v178, v194
	v_div_fixup_f32 v150, v186, v158, 1.0
	v_div_scale_f32 v187, vcc, 1.0, v159, 1.0
	v_mul_f32_e32 v195, v187, v179
	v_fma_f32 v151, -v167, v195, v187
	v_fmac_f32_e32 v195, v151, v179
	v_fma_f32 v187, -v167, v195, v187
	v_div_fmas_f32 v187, v187, v179, v195
	v_div_fixup_f32 v151, v187, v159, 1.0
	v_div_scale_f32 v188, vcc, 1.0, v160, 1.0
	v_mul_f32_e32 v196, v188, v180
	v_fma_f32 v152, -v172, v196, v188
	v_fmac_f32_e32 v196, v152, v180
	v_fma_f32 v188, -v172, v196, v188
	v_div_fmas_f32 v188, v188, v180, v196
	v_div_fixup_f32 v152, v188, v160, 1.0
	v_div_scale_f32 v189, vcc, 1.0, v161, 1.0
	v_mul_f32_e32 v197, v189, v181
	v_fma_f32 v153, -v173, v197, v189
	v_fmac_f32_e32 v197, v153, v181
	v_fma_f32 v189, -v173, v197, v189
	v_div_fmas_f32 v189, v189, v181, v197
	v_div_fixup_f32 v153, v189, v161, 1.0
	v_div_scale_f32 v190, vcc, 1.0, v162, 1.0
	v_mul_f32_e32 v198, v190, v182
	v_fma_f32 v154, -v174, v198, v190
	v_fmac_f32_e32 v198, v154, v182
	v_fma_f32 v190, -v174, v198, v190
	v_div_fmas_f32 v190, v190, v182, v198
	v_div_fixup_f32 v154, v190, v162, 1.0
	v_div_scale_f32 v191, vcc, 1.0, v163, 1.0
	v_mul_f32_e32 v199, v191, v183
	v_fma_f32 v155, -v175, v199, v191
	v_fmac_f32_e32 v199, v155, v183
	v_fma_f32 v191, -v175, v199, v191
	v_div_fmas_f32 v191, v191, v183, v199
	v_div_fixup_f32 v155, v191, v163, 1.0
	v_cvt_pk_bf16_f32 v200, v148, v149
	v_cvt_pk_bf16_f32 v201, v150, v151
	v_cvt_pk_bf16_f32 v202, v152, v153
	v_cvt_pk_bf16_f32 v203, v154, v155
	global_store_dwordx4 v243, v[200:203], s[84:85]
	s_add_u32 s84, s84, 0x1000
	s_addc_u32 s85, s85, 0
	v_add_f32_e32 v148, v56, v136
	v_add_f32_e32 v149, v57, v137
	v_add_f32_e32 v150, v58, v138
	v_add_f32_e32 v151, v59, v139
	v_add_f32_e32 v152, v60, v140
	v_add_f32_e32 v153, v61, v141
	v_add_f32_e32 v154, v62, v142
	v_add_f32_e32 v155, v63, v143
	v_mul_f32_e32 v148, 0xbfb8aa3b, v148
	v_mul_f32_e32 v149, 0xbfb8aa3b, v149
	v_mul_f32_e32 v150, 0xbfb8aa3b, v150
	v_mul_f32_e32 v151, 0xbfb8aa3b, v151
	v_mul_f32_e32 v152, 0xbfb8aa3b, v152
	v_mul_f32_e32 v153, 0xbfb8aa3b, v153
	v_mul_f32_e32 v154, 0xbfb8aa3b, v154
	v_mul_f32_e32 v155, 0xbfb8aa3b, v155
	v_exp_f32_e32 v156, v148
	v_exp_f32_e32 v157, v149
	v_exp_f32_e32 v158, v150
	v_exp_f32_e32 v159, v151
	v_exp_f32_e32 v160, v152
	v_exp_f32_e32 v161, v153
	v_exp_f32_e32 v162, v154
	v_exp_f32_e32 v163, v155
	v_add_f32_e32 v156, 1.0, v156
	v_add_f32_e32 v157, 1.0, v157
	v_add_f32_e32 v158, 1.0, v158
	v_add_f32_e32 v159, 1.0, v159
	v_add_f32_e32 v160, 1.0, v160
	v_add_f32_e32 v161, 1.0, v161
	v_add_f32_e32 v162, 1.0, v162
	v_add_f32_e32 v163, 1.0, v163
	v_div_scale_f32 v164, s[76:77], v156, v156, 1.0
	v_div_scale_f32 v165, s[76:77], v157, v157, 1.0
	v_div_scale_f32 v166, s[76:77], v158, v158, 1.0
	v_div_scale_f32 v167, s[76:77], v159, v159, 1.0
	v_div_scale_f32 v172, s[76:77], v160, v160, 1.0
	v_div_scale_f32 v173, s[76:77], v161, v161, 1.0
	v_div_scale_f32 v174, s[76:77], v162, v162, 1.0
	v_div_scale_f32 v175, s[76:77], v163, v163, 1.0
	v_rcp_f32_e32 v176, v164
	v_rcp_f32_e32 v177, v165
	v_rcp_f32_e32 v178, v166
	v_rcp_f32_e32 v179, v167
	v_rcp_f32_e32 v180, v172
	v_rcp_f32_e32 v181, v173
	v_rcp_f32_e32 v182, v174
	v_rcp_f32_e32 v183, v175
	v_fma_f32 v148, -v164, v176, 1.0
	v_fma_f32 v149, -v165, v177, 1.0
	v_fma_f32 v150, -v166, v178, 1.0
	v_fma_f32 v151, -v167, v179, 1.0
	v_fma_f32 v152, -v172, v180, 1.0
	v_fma_f32 v153, -v173, v181, 1.0
	v_fma_f32 v154, -v174, v182, 1.0
	v_fma_f32 v155, -v175, v183, 1.0
	v_fmac_f32_e32 v176, v148, v176
	v_fmac_f32_e32 v177, v149, v177
	v_fmac_f32_e32 v178, v150, v178
	v_fmac_f32_e32 v179, v151, v179
	v_fmac_f32_e32 v180, v152, v180
	v_fmac_f32_e32 v181, v153, v181
	v_fmac_f32_e32 v182, v154, v182
	v_fmac_f32_e32 v183, v155, v183
	v_div_scale_f32 v184, vcc, 1.0, v156, 1.0
	v_mul_f32_e32 v192, v184, v176
	v_fma_f32 v148, -v164, v192, v184
	v_fmac_f32_e32 v192, v148, v176
	v_fma_f32 v184, -v164, v192, v184
	v_div_fmas_f32 v184, v184, v176, v192
	v_div_fixup_f32 v148, v184, v156, 1.0
	v_div_scale_f32 v185, vcc, 1.0, v157, 1.0
	v_mul_f32_e32 v193, v185, v177
	v_fma_f32 v149, -v165, v193, v185
	v_fmac_f32_e32 v193, v149, v177
	v_fma_f32 v185, -v165, v193, v185
	v_div_fmas_f32 v185, v185, v177, v193
	v_div_fixup_f32 v149, v185, v157, 1.0
	v_div_scale_f32 v186, vcc, 1.0, v158, 1.0
	v_mul_f32_e32 v194, v186, v178
	v_fma_f32 v150, -v166, v194, v186
	v_fmac_f32_e32 v194, v150, v178
	v_fma_f32 v186, -v166, v194, v186
	v_div_fmas_f32 v186, v186, v178, v194
	v_div_fixup_f32 v150, v186, v158, 1.0
	v_div_scale_f32 v187, vcc, 1.0, v159, 1.0
	v_mul_f32_e32 v195, v187, v179
	v_fma_f32 v151, -v167, v195, v187
	v_fmac_f32_e32 v195, v151, v179
	v_fma_f32 v187, -v167, v195, v187
	v_div_fmas_f32 v187, v187, v179, v195
	v_div_fixup_f32 v151, v187, v159, 1.0
	v_div_scale_f32 v188, vcc, 1.0, v160, 1.0
	v_mul_f32_e32 v196, v188, v180
	v_fma_f32 v152, -v172, v196, v188
	v_fmac_f32_e32 v196, v152, v180
	v_fma_f32 v188, -v172, v196, v188
	v_div_fmas_f32 v188, v188, v180, v196
	v_div_fixup_f32 v152, v188, v160, 1.0
	v_div_scale_f32 v189, vcc, 1.0, v161, 1.0
	v_mul_f32_e32 v197, v189, v181
	v_fma_f32 v153, -v173, v197, v189
	v_fmac_f32_e32 v197, v153, v181
	v_fma_f32 v189, -v173, v197, v189
	v_div_fmas_f32 v189, v189, v181, v197
	v_div_fixup_f32 v153, v189, v161, 1.0
	v_div_scale_f32 v190, vcc, 1.0, v162, 1.0
	v_mul_f32_e32 v198, v190, v182
	v_fma_f32 v154, -v174, v198, v190
	v_fmac_f32_e32 v198, v154, v182
	v_fma_f32 v190, -v174, v198, v190
	v_div_fmas_f32 v190, v190, v182, v198
	v_div_fixup_f32 v154, v190, v162, 1.0
	v_div_scale_f32 v191, vcc, 1.0, v163, 1.0
	v_mul_f32_e32 v199, v191, v183
	v_fma_f32 v155, -v175, v199, v191
	v_fmac_f32_e32 v199, v155, v183
	v_fma_f32 v191, -v175, v199, v191
	v_div_fmas_f32 v191, v191, v183, v199
	v_div_fixup_f32 v155, v191, v163, 1.0
	v_cvt_pk_bf16_f32 v204, v148, v149
	v_cvt_pk_bf16_f32 v205, v150, v151
	v_cvt_pk_bf16_f32 v206, v152, v153
	v_cvt_pk_bf16_f32 v207, v154, v155
	global_store_dwordx4 v243, v[204:207], s[84:85]
	s_add_u32 s84, s84, 0x1000
	s_addc_u32 s85, s85, 0
	s_cmp_eq_u32 s83, 1
	s_cbranch_scc1 .Lp6a_epdone
	s_cmp_eq_u32 s95, 1
	s_cbranch_scc0 .Lp6a_epdone
	v_mov_b32_e32 v0, v64
	v_mov_b32_e32 v1, v65
	v_mov_b32_e32 v2, v66
	v_mov_b32_e32 v3, v67
	v_mov_b32_e32 v4, v68
	v_mov_b32_e32 v5, v69
	v_mov_b32_e32 v6, v70
	v_mov_b32_e32 v7, v71
	v_mov_b32_e32 v8, v72
	v_mov_b32_e32 v9, v73
	v_mov_b32_e32 v10, v74
	v_mov_b32_e32 v11, v75
	v_mov_b32_e32 v12, v76
	v_mov_b32_e32 v13, v77
	v_mov_b32_e32 v14, v78
	v_mov_b32_e32 v15, v79
	v_mov_b32_e32 v16, v80
	v_mov_b32_e32 v17, v81
	v_mov_b32_e32 v18, v82
	v_mov_b32_e32 v19, v83
	v_mov_b32_e32 v20, v84
	v_mov_b32_e32 v21, v85
	v_mov_b32_e32 v22, v86
	v_mov_b32_e32 v23, v87
	v_mov_b32_e32 v24, v88
	v_mov_b32_e32 v25, v89
	v_mov_b32_e32 v26, v90
	v_mov_b32_e32 v27, v91
	v_mov_b32_e32 v28, v92
	v_mov_b32_e32 v29, v93
	v_mov_b32_e32 v30, v94
	v_mov_b32_e32 v31, v95
	v_mov_b32_e32 v32, v96
	v_mov_b32_e32 v33, v97
	v_mov_b32_e32 v34, v98
	v_mov_b32_e32 v35, v99
	v_mov_b32_e32 v36, v100
	v_mov_b32_e32 v37, v101
	v_mov_b32_e32 v38, v102
	v_mov_b32_e32 v39, v103
	v_mov_b32_e32 v40, v104
	v_mov_b32_e32 v41, v105
	v_mov_b32_e32 v42, v106
	v_mov_b32_e32 v43, v107
	v_mov_b32_e32 v44, v108
	v_mov_b32_e32 v45, v109
	v_mov_b32_e32 v46, v110
	v_mov_b32_e32 v47, v111
	v_mov_b32_e32 v48, v112
	v_mov_b32_e32 v49, v113
	v_mov_b32_e32 v50, v114
	v_mov_b32_e32 v51, v115
	v_mov_b32_e32 v52, v116
	v_mov_b32_e32 v53, v117
	v_mov_b32_e32 v54, v118
	v_mov_b32_e32 v55, v119
	v_mov_b32_e32 v56, v120
	v_mov_b32_e32 v57, v121
	v_mov_b32_e32 v58, v122
	v_mov_b32_e32 v59, v123
	v_mov_b32_e32 v60, v124
	v_mov_b32_e32 v61, v125
	v_mov_b32_e32 v62, v126
	v_mov_b32_e32 v63, v127
	s_mov_b32 s83, 1
	s_branch .Lp6a_ep

.Lp6b_ep:
	s_lshl_b32 s71, s83, 16
	s_add_u32 s86, s24, s71
	s_addc_u32 s87, s25, 0
	s_lshl_b32 s71, s83, 16
	s_add_u32 s84, s24, s71
	s_addc_u32 s85, s25, 0
	global_load_dwordx4 v[128:131], v243, s[86:87]
	s_add_u32 s86, s86, 0x1000
	s_addc_u32 s87, s87, 0
	global_load_dwordx4 v[132:135], v243, s[86:87]
	s_add_u32 s86, s86, 0x1000
	s_addc_u32 s87, s87, 0
	global_load_dwordx4 v[136:139], v243, s[86:87]
	s_add_u32 s86, s86, 0x1000
	s_addc_u32 s87, s87, 0
	global_load_dwordx4 v[140:143], v243, s[86:87]
	s_add_u32 s86, s86, 0x1000
	s_addc_u32 s87, s87, 0
	global_load_dwordx4 v[148:151], v243, s[86:87]
	s_add_u32 s86, s86, 0x1000
	s_addc_u32 s87, s87, 0
	global_load_dwordx4 v[152:155], v243, s[86:87]
	s_add_u32 s86, s86, 0x1000
	s_addc_u32 s87, s87, 0
	global_load_dwordx4 v[156:159], v243, s[86:87]
	s_add_u32 s86, s86, 0x1000
	s_addc_u32 s87, s87, 0
	global_load_dwordx4 v[160:163], v243, s[86:87]
	s_add_u32 s86, s86, 0x1000
	s_addc_u32 s87, s87, 0
	s_waitcnt vmcnt(7)
	v_lshlrev_b32_e32 v164, 16, v128
	v_and_b32_e32 v165, 0xffff0000, v128
	v_lshlrev_b32_e32 v166, 16, v129
	v_and_b32_e32 v167, 0xffff0000, v129
	v_lshlrev_b32_e32 v172, 16, v130
	v_and_b32_e32 v173, 0xffff0000, v130
	v_lshlrev_b32_e32 v174, 16, v131
	v_and_b32_e32 v175, 0xffff0000, v131
	v_mul_f32_e32 v164, v0, v164
	v_mul_f32_e32 v165, v1, v165
	v_mul_f32_e32 v166, v2, v166
	v_mul_f32_e32 v167, v3, v167
	v_mul_f32_e32 v172, v4, v172
	v_mul_f32_e32 v173, v5, v173
	v_mul_f32_e32 v174, v6, v174
	v_mul_f32_e32 v175, v7, v175
	v_cvt_pk_bf16_f32 v184, v164, v165
	v_cvt_pk_bf16_f32 v185, v166, v167
	v_cvt_pk_bf16_f32 v186, v172, v173
	v_cvt_pk_bf16_f32 v187, v174, v175
	global_store_dwordx4 v243, v[184:187], s[84:85]
	s_add_u32 s84, s84, 0x1000
	s_addc_u32 s85, s85, 0
	s_waitcnt vmcnt(7)
	v_lshlrev_b32_e32 v164, 16, v132
	v_and_b32_e32 v165, 0xffff0000, v132
	v_lshlrev_b32_e32 v166, 16, v133
	v_and_b32_e32 v167, 0xffff0000, v133
	v_lshlrev_b32_e32 v172, 16, v134
	v_and_b32_e32 v173, 0xffff0000, v134
	v_lshlrev_b32_e32 v174, 16, v135
	v_and_b32_e32 v175, 0xffff0000, v135
	v_mul_f32_e32 v164, v8, v164
	v_mul_f32_e32 v165, v9, v165
	v_mul_f32_e32 v166, v10, v166
	v_mul_f32_e32 v167, v11, v167
	v_mul_f32_e32 v172, v12, v172
	v_mul_f32_e32 v173, v13, v173
	v_mul_f32_e32 v174, v14, v174
	v_mul_f32_e32 v175, v15, v175
	v_cvt_pk_bf16_f32 v188, v164, v165
	v_cvt_pk_bf16_f32 v189, v166, v167
	v_cvt_pk_bf16_f32 v190, v172, v173
	v_cvt_pk_bf16_f32 v191, v174, v175
	global_store_dwordx4 v243, v[188:191], s[84:85]
	s_add_u32 s84, s84, 0x1000
	s_addc_u32 s85, s85, 0
	s_waitcnt vmcnt(7)
	v_lshlrev_b32_e32 v164, 16, v136
	v_and_b32_e32 v165, 0xffff0000, v136
	v_lshlrev_b32_e32 v166, 16, v137
	v_and_b32_e32 v167, 0xffff0000, v137
	v_lshlrev_b32_e32 v172, 16, v138
	v_and_b32_e32 v173, 0xffff0000, v138
	v_lshlrev_b32_e32 v174, 16, v139
	v_and_b32_e32 v175, 0xffff0000, v139
	v_mul_f32_e32 v164, v16, v164
	v_mul_f32_e32 v165, v17, v165
	v_mul_f32_e32 v166, v18, v166
	v_mul_f32_e32 v167, v19, v167
	v_mul_f32_e32 v172, v20, v172
	v_mul_f32_e32 v173, v21, v173
	v_mul_f32_e32 v174, v22, v174
	v_mul_f32_e32 v175, v23, v175
	v_cvt_pk_bf16_f32 v184, v164, v165
	v_cvt_pk_bf16_f32 v185, v166, v167
	v_cvt_pk_bf16_f32 v186, v172, v173
	v_cvt_pk_bf16_f32 v187, v174, v175
	global_store_dwordx4 v243, v[184:187], s[84:85]
	s_add_u32 s84, s84, 0x1000
	s_addc_u32 s85, s85, 0
	s_waitcnt vmcnt(7)
	v_lshlrev_b32_e32 v164, 16, v140
	v_and_b32_e32 v165, 0xffff0000, v140
	v_lshlrev_b32_e32 v166, 16, v141
	v_and_b32_e32 v167, 0xffff0000, v141
	v_lshlrev_b32_e32 v172, 16, v142
	v_and_b32_e32 v173, 0xffff0000, v142
	v_lshlrev_b32_e32 v174, 16, v143
	v_and_b32_e32 v175, 0xffff0000, v143
	v_mul_f32_e32 v164, v24, v164
	v_mul_f32_e32 v165, v25, v165
	v_mul_f32_e32 v166, v26, v166
	v_mul_f32_e32 v167, v27, v167
	v_mul_f32_e32 v172, v28, v172
	v_mul_f32_e32 v173, v29, v173
	v_mul_f32_e32 v174, v30, v174
	v_mul_f32_e32 v175, v31, v175
	v_cvt_pk_bf16_f32 v188, v164, v165
	v_cvt_pk_bf16_f32 v189, v166, v167
	v_cvt_pk_bf16_f32 v190, v172, v173
	v_cvt_pk_bf16_f32 v191, v174, v175
	global_store_dwordx4 v243, v[188:191], s[84:85]
	s_add_u32 s84, s84, 0x1000
	s_addc_u32 s85, s85, 0
	s_waitcnt vmcnt(7)
	v_lshlrev_b32_e32 v164, 16, v148
	v_and_b32_e32 v165, 0xffff0000, v148
	v_lshlrev_b32_e32 v166, 16, v149
	v_and_b32_e32 v167, 0xffff0000, v149
	v_lshlrev_b32_e32 v172, 16, v150
	v_and_b32_e32 v173, 0xffff0000, v150
	v_lshlrev_b32_e32 v174, 16, v151
	v_and_b32_e32 v175, 0xffff0000, v151
	v_mul_f32_e32 v164, v32, v164
	v_mul_f32_e32 v165, v33, v165
	v_mul_f32_e32 v166, v34, v166
	v_mul_f32_e32 v167, v35, v167
	v_mul_f32_e32 v172, v36, v172
	v_mul_f32_e32 v173, v37, v173
	v_mul_f32_e32 v174, v38, v174
	v_mul_f32_e32 v175, v39, v175
	v_cvt_pk_bf16_f32 v184, v164, v165
	v_cvt_pk_bf16_f32 v185, v166, v167
	v_cvt_pk_bf16_f32 v186, v172, v173
	v_cvt_pk_bf16_f32 v187, v174, v175
	global_store_dwordx4 v243, v[184:187], s[84:85]
	s_add_u32 s84, s84, 0x1000
	s_addc_u32 s85, s85, 0
	s_waitcnt vmcnt(7)
	v_lshlrev_b32_e32 v164, 16, v152
	v_and_b32_e32 v165, 0xffff0000, v152
	v_lshlrev_b32_e32 v166, 16, v153
	v_and_b32_e32 v167, 0xffff0000, v153
	v_lshlrev_b32_e32 v172, 16, v154
	v_and_b32_e32 v173, 0xffff0000, v154
	v_lshlrev_b32_e32 v174, 16, v155
	v_and_b32_e32 v175, 0xffff0000, v155
	v_mul_f32_e32 v164, v40, v164
	v_mul_f32_e32 v165, v41, v165
	v_mul_f32_e32 v166, v42, v166
	v_mul_f32_e32 v167, v43, v167
	v_mul_f32_e32 v172, v44, v172
	v_mul_f32_e32 v173, v45, v173
	v_mul_f32_e32 v174, v46, v174
	v_mul_f32_e32 v175, v47, v175
	v_cvt_pk_bf16_f32 v188, v164, v165
	v_cvt_pk_bf16_f32 v189, v166, v167
	v_cvt_pk_bf16_f32 v190, v172, v173
	v_cvt_pk_bf16_f32 v191, v174, v175
	global_store_dwordx4 v243, v[188:191], s[84:85]
	s_add_u32 s84, s84, 0x1000
	s_addc_u32 s85, s85, 0
	s_waitcnt vmcnt(7)
	v_lshlrev_b32_e32 v164, 16, v156
	v_and_b32_e32 v165, 0xffff0000, v156
	v_lshlrev_b32_e32 v166, 16, v157
	v_and_b32_e32 v167, 0xffff0000, v157
	v_lshlrev_b32_e32 v172, 16, v158
	v_and_b32_e32 v173, 0xffff0000, v158
	v_lshlrev_b32_e32 v174, 16, v159
	v_and_b32_e32 v175, 0xffff0000, v159
	v_mul_f32_e32 v164, v48, v164
	v_mul_f32_e32 v165, v49, v165
	v_mul_f32_e32 v166, v50, v166
	v_mul_f32_e32 v167, v51, v167
	v_mul_f32_e32 v172, v52, v172
	v_mul_f32_e32 v173, v53, v173
	v_mul_f32_e32 v174, v54, v174
	v_mul_f32_e32 v175, v55, v175
	v_cvt_pk_bf16_f32 v184, v164, v165
	v_cvt_pk_bf16_f32 v185, v166, v167
	v_cvt_pk_bf16_f32 v186, v172, v173
	v_cvt_pk_bf16_f32 v187, v174, v175
	global_store_dwordx4 v243, v[184:187], s[84:85]
	s_add_u32 s84, s84, 0x1000
	s_addc_u32 s85, s85, 0
	s_waitcnt vmcnt(7)
	v_lshlrev_b32_e32 v164, 16, v160
	v_and_b32_e32 v165, 0xffff0000, v160
	v_lshlrev_b32_e32 v166, 16, v161
	v_and_b32_e32 v167, 0xffff0000, v161
	v_lshlrev_b32_e32 v172, 16, v162
	v_and_b32_e32 v173, 0xffff0000, v162
	v_lshlrev_b32_e32 v174, 16, v163
	v_and_b32_e32 v175, 0xffff0000, v163
	v_mul_f32_e32 v164, v56, v164
	v_mul_f32_e32 v165, v57, v165
	v_mul_f32_e32 v166, v58, v166
	v_mul_f32_e32 v167, v59, v167
	v_mul_f32_e32 v172, v60, v172
	v_mul_f32_e32 v173, v61, v173
	v_mul_f32_e32 v174, v62, v174
	v_mul_f32_e32 v175, v63, v175
	v_cvt_pk_bf16_f32 v188, v164, v165
	v_cvt_pk_bf16_f32 v189, v166, v167
	v_cvt_pk_bf16_f32 v190, v172, v173
	v_cvt_pk_bf16_f32 v191, v174, v175
	global_store_dwordx4 v243, v[188:191], s[84:85]
	s_add_u32 s84, s84, 0x1000
	s_addc_u32 s85, s85, 0
	s_cmp_eq_u32 s83, 1
	s_cbranch_scc1 .Lp6b_epdone
	s_cmp_eq_u32 s95, 1
	s_cbranch_scc0 .Lp6b_epdone
	v_mov_b32_e32 v0, v64
	v_mov_b32_e32 v1, v65
	v_mov_b32_e32 v2, v66
	v_mov_b32_e32 v3, v67
	v_mov_b32_e32 v4, v68
	v_mov_b32_e32 v5, v69
	v_mov_b32_e32 v6, v70
	v_mov_b32_e32 v7, v71
	v_mov_b32_e32 v8, v72
	v_mov_b32_e32 v9, v73
	v_mov_b32_e32 v10, v74
	v_mov_b32_e32 v11, v75
	v_mov_b32_e32 v12, v76
	v_mov_b32_e32 v13, v77
	v_mov_b32_e32 v14, v78
	v_mov_b32_e32 v15, v79
	v_mov_b32_e32 v16, v80
	v_mov_b32_e32 v17, v81
	v_mov_b32_e32 v18, v82
	v_mov_b32_e32 v19, v83
	v_mov_b32_e32 v20, v84
	v_mov_b32_e32 v21, v85
	v_mov_b32_e32 v22, v86
	v_mov_b32_e32 v23, v87
	v_mov_b32_e32 v24, v88
	v_mov_b32_e32 v25, v89
	v_mov_b32_e32 v26, v90
	v_mov_b32_e32 v27, v91
	v_mov_b32_e32 v28, v92
	v_mov_b32_e32 v29, v93
	v_mov_b32_e32 v30, v94
	v_mov_b32_e32 v31, v95
	v_mov_b32_e32 v32, v96
	v_mov_b32_e32 v33, v97
	v_mov_b32_e32 v34, v98
	v_mov_b32_e32 v35, v99
	v_mov_b32_e32 v36, v100
	v_mov_b32_e32 v37, v101
	v_mov_b32_e32 v38, v102
	v_mov_b32_e32 v39, v103
	v_mov_b32_e32 v40, v104
	v_mov_b32_e32 v41, v105
	v_mov_b32_e32 v42, v106
	v_mov_b32_e32 v43, v107
	v_mov_b32_e32 v44, v108
	v_mov_b32_e32 v45, v109
	v_mov_b32_e32 v46, v110
	v_mov_b32_e32 v47, v111
	v_mov_b32_e32 v48, v112
	v_mov_b32_e32 v49, v113
	v_mov_b32_e32 v50, v114
	v_mov_b32_e32 v51, v115
	v_mov_b32_e32 v52, v116
	v_mov_b32_e32 v53, v117
	v_mov_b32_e32 v54, v118
	v_mov_b32_e32 v55, v119
	v_mov_b32_e32 v56, v120
	v_mov_b32_e32 v57, v121
	v_mov_b32_e32 v58, v122
	v_mov_b32_e32 v59, v123
	v_mov_b32_e32 v60, v124
	v_mov_b32_e32 v61, v125
	v_mov_b32_e32 v62, v126
	v_mov_b32_e32 v63, v127
	s_mov_b32 s83, 1
	s_branch .Lp6b_ep

.Lp6c_ep:
	s_lshl_b32 s71, s83, 16
	s_add_u32 s71, s71, 0x8000
	s_add_u32 s84, s24, s71
	s_addc_u32 s85, s25, 0
	v_cvt_pk_bf16_f32 v136, v0, v1
	v_cvt_pk_bf16_f32 v137, v2, v3
	v_cvt_pk_bf16_f32 v138, v4, v5
	v_cvt_pk_bf16_f32 v139, v6, v7
	global_store_dwordx4 v243, v[136:139], s[84:85]
	s_add_u32 s84, s84, 0x1000
	s_addc_u32 s85, s85, 0
	v_cvt_pk_bf16_f32 v140, v8, v9
	v_cvt_pk_bf16_f32 v141, v10, v11
	v_cvt_pk_bf16_f32 v142, v12, v13
	v_cvt_pk_bf16_f32 v143, v14, v15
	global_store_dwordx4 v243, v[140:143], s[84:85]
	s_add_u32 s84, s84, 0x1000
	s_addc_u32 s85, s85, 0
	v_cvt_pk_bf16_f32 v136, v16, v17
	v_cvt_pk_bf16_f32 v137, v18, v19
	v_cvt_pk_bf16_f32 v138, v20, v21
	v_cvt_pk_bf16_f32 v139, v22, v23
	global_store_dwordx4 v243, v[136:139], s[84:85]
	s_add_u32 s84, s84, 0x1000
	s_addc_u32 s85, s85, 0
	v_cvt_pk_bf16_f32 v140, v24, v25
	v_cvt_pk_bf16_f32 v141, v26, v27
	v_cvt_pk_bf16_f32 v142, v28, v29
	v_cvt_pk_bf16_f32 v143, v30, v31
	global_store_dwordx4 v243, v[140:143], s[84:85]
	s_add_u32 s84, s84, 0x1000
	s_addc_u32 s85, s85, 0
	v_cvt_pk_bf16_f32 v136, v32, v33
	v_cvt_pk_bf16_f32 v137, v34, v35
	v_cvt_pk_bf16_f32 v138, v36, v37
	v_cvt_pk_bf16_f32 v139, v38, v39
	global_store_dwordx4 v243, v[136:139], s[84:85]
	s_add_u32 s84, s84, 0x1000
	s_addc_u32 s85, s85, 0
	v_cvt_pk_bf16_f32 v140, v40, v41
	v_cvt_pk_bf16_f32 v141, v42, v43
	v_cvt_pk_bf16_f32 v142, v44, v45
	v_cvt_pk_bf16_f32 v143, v46, v47
	global_store_dwordx4 v243, v[140:143], s[84:85]
	s_add_u32 s84, s84, 0x1000
	s_addc_u32 s85, s85, 0
	v_cvt_pk_bf16_f32 v136, v48, v49
	v_cvt_pk_bf16_f32 v137, v50, v51
	v_cvt_pk_bf16_f32 v138, v52, v53
	v_cvt_pk_bf16_f32 v139, v54, v55
	global_store_dwordx4 v243, v[136:139], s[84:85]
	s_add_u32 s84, s84, 0x1000
	s_addc_u32 s85, s85, 0
	v_cvt_pk_bf16_f32 v140, v56, v57
	v_cvt_pk_bf16_f32 v141, v58, v59
	v_cvt_pk_bf16_f32 v142, v60, v61
	v_cvt_pk_bf16_f32 v143, v62, v63
	global_store_dwordx4 v243, v[140:143], s[84:85]
	s_add_u32 s84, s84, 0x1000
	s_addc_u32 s85, s85, 0
	s_cmp_eq_u32 s83, 1
	s_cbranch_scc1 .Lp6c_epdone
	s_cmp_eq_u32 s95, 1
	s_cbranch_scc0 .Lp6c_epdone
	v_mov_b32_e32 v0, v64
	v_mov_b32_e32 v1, v65
	v_mov_b32_e32 v2, v66
	v_mov_b32_e32 v3, v67
	v_mov_b32_e32 v4, v68
	v_mov_b32_e32 v5, v69
	v_mov_b32_e32 v6, v70
	v_mov_b32_e32 v7, v71
	v_mov_b32_e32 v8, v72
	v_mov_b32_e32 v9, v73
	v_mov_b32_e32 v10, v74
	v_mov_b32_e32 v11, v75
	v_mov_b32_e32 v12, v76
	v_mov_b32_e32 v13, v77
	v_mov_b32_e32 v14, v78
	v_mov_b32_e32 v15, v79
	v_mov_b32_e32 v16, v80
	v_mov_b32_e32 v17, v81
	v_mov_b32_e32 v18, v82
	v_mov_b32_e32 v19, v83
	v_mov_b32_e32 v20, v84
	v_mov_b32_e32 v21, v85
	v_mov_b32_e32 v22, v86
	v_mov_b32_e32 v23, v87
	v_mov_b32_e32 v24, v88
	v_mov_b32_e32 v25, v89
	v_mov_b32_e32 v26, v90
	v_mov_b32_e32 v27, v91
	v_mov_b32_e32 v28, v92
	v_mov_b32_e32 v29, v93
	v_mov_b32_e32 v30, v94
	v_mov_b32_e32 v31, v95
	v_mov_b32_e32 v32, v96
	v_mov_b32_e32 v33, v97
	v_mov_b32_e32 v34, v98
	v_mov_b32_e32 v35, v99
	v_mov_b32_e32 v36, v100
	v_mov_b32_e32 v37, v101
	v_mov_b32_e32 v38, v102
	v_mov_b32_e32 v39, v103
	v_mov_b32_e32 v40, v104
	v_mov_b32_e32 v41, v105
	v_mov_b32_e32 v42, v106
	v_mov_b32_e32 v43, v107
	v_mov_b32_e32 v44, v108
	v_mov_b32_e32 v45, v109
	v_mov_b32_e32 v46, v110
	v_mov_b32_e32 v47, v111
	v_mov_b32_e32 v48, v112
	v_mov_b32_e32 v49, v113
	v_mov_b32_e32 v50, v114
	v_mov_b32_e32 v51, v115
	v_mov_b32_e32 v52, v116
	v_mov_b32_e32 v53, v117
	v_mov_b32_e32 v54, v118
	v_mov_b32_e32 v55, v119
	v_mov_b32_e32 v56, v120
	v_mov_b32_e32 v57, v121
	v_mov_b32_e32 v58, v122
	v_mov_b32_e32 v59, v123
	v_mov_b32_e32 v60, v124
	v_mov_b32_e32 v61, v125
	v_mov_b32_e32 v62, v126
	v_mov_b32_e32 v63, v127
	s_mov_b32 s83, 1
	s_branch .Lp6c_ep

.Lp6d_ep:
	s_add_u32 s28, s22, 0x1000
	s_addc_u32 s29, s23, 0
	global_load_dwordx4 v[128:131], v244, s[28:29]
	global_load_dwordx4 v[132:135], v244, s[28:29] offset:64
	global_load_dwordx4 v[136:139], v244, s[28:29] offset:128
	global_load_dwordx4 v[140:143], v244, s[28:29] offset:192
	s_cmp_eq_u32 s83, 1
	s_cselect_b32 s75, s97, s70
	v_lshrrev_b32_e32 v249, 1, v168
	v_and_b32_e32 v249, 0x1c0, v249
	v_and_b32_e32 v250, 15, v168
	v_or_b32_e32 v249, v249, v250
	v_lshl_add_u32 v249, s75, 7, v249
	v_lshlrev_b32_e32 v249, 11, v249
	v_bfe_u32 v250, v168, 4, 2
	v_lshlrev_b32_e32 v246, 3, v250
	v_and_b32_e32 v250, 1, v250
	v_mul_u32_u24_e32 v250, 24, v250
	v_add3_u32 v249, v249, v250, v246
	v_bfe_u32 v250, v168, 6, 1
	s_lshl_b32 s71, s74, 8
	v_lshl_add_u32 v245, v250, 7, v249
	v_add_u32_e32 v245, s71, v245
	v_add_u32_e32 v246, 0x8000, v245
	v_add_u32_e32 v247, 0x10000, v245
	v_add_u32_e32 v248, 0x18000, v245
	s_lshl_b32 s71, s83, 16
	s_add_u32 s86, s24, s71
	s_addc_u32 s87, s25, 0
	s_lshl_b32 s71, s83, 16
	s_add_u32 s71, s71, 0x8000
	s_add_u32 s88, s24, s71
	s_addc_u32 s89, s25, 0
	global_load_dwordx4 v[148:151], v243, s[86:87]
	s_add_u32 s86, s86, 0x1000
	s_addc_u32 s87, s87, 0
	global_load_dwordx4 v[164:167], v243, s[88:89]
	s_add_u32 s88, s88, 0x1000
	s_addc_u32 s89, s89, 0
	global_load_dwordx4 v[152:155], v243, s[86:87]
	s_add_u32 s86, s86, 0x1000
	s_addc_u32 s87, s87, 0
	global_load_dwordx4 v[172:175], v243, s[88:89]
	s_add_u32 s88, s88, 0x1000
	s_addc_u32 s89, s89, 0
	global_load_dwordx4 v[156:159], v243, s[86:87]
	s_add_u32 s86, s86, 0x1000
	s_addc_u32 s87, s87, 0
	global_load_dwordx4 v[176:179], v243, s[88:89]
	s_add_u32 s88, s88, 0x1000
	s_addc_u32 s89, s89, 0
	global_load_dwordx4 v[160:163], v243, s[86:87]
	s_add_u32 s86, s86, 0x1000
	s_addc_u32 s87, s87, 0
	global_load_dwordx4 v[180:183], v243, s[88:89]
	s_add_u32 s88, s88, 0x1000
	s_addc_u32 s89, s89, 0
	s_waitcnt vmcnt(6)
	v_add_f32_e32 v184, v0, v128
	v_add_f32_e32 v185, v1, v129
	v_add_f32_e32 v186, v2, v130
	v_add_f32_e32 v187, v3, v131
	v_add_f32_e32 v188, v4, v132
	v_add_f32_e32 v189, v5, v133
	v_add_f32_e32 v190, v6, v134
	v_add_f32_e32 v191, v7, v135
	v_mul_f32_e32 v184, 0xbfb8aa3b, v184
	v_mul_f32_e32 v185, 0xbfb8aa3b, v185
	v_mul_f32_e32 v186, 0xbfb8aa3b, v186
	v_mul_f32_e32 v187, 0xbfb8aa3b, v187
	v_mul_f32_e32 v188, 0xbfb8aa3b, v188
	v_mul_f32_e32 v189, 0xbfb8aa3b, v189
	v_mul_f32_e32 v190, 0xbfb8aa3b, v190
	v_mul_f32_e32 v191, 0xbfb8aa3b, v191
	v_exp_f32_e32 v192, v184
	v_exp_f32_e32 v193, v185
	v_exp_f32_e32 v194, v186
	v_exp_f32_e32 v195, v187
	v_exp_f32_e32 v196, v188
	v_exp_f32_e32 v197, v189
	v_exp_f32_e32 v198, v190
	v_exp_f32_e32 v199, v191
	v_add_f32_e32 v192, 1.0, v192
	v_add_f32_e32 v193, 1.0, v193
	v_add_f32_e32 v194, 1.0, v194
	v_add_f32_e32 v195, 1.0, v195
	v_add_f32_e32 v196, 1.0, v196
	v_add_f32_e32 v197, 1.0, v197
	v_add_f32_e32 v198, 1.0, v198
	v_add_f32_e32 v199, 1.0, v199
	v_div_scale_f32 v200, s[76:77], v192, v192, 1.0
	v_div_scale_f32 v201, s[76:77], v193, v193, 1.0
	v_div_scale_f32 v202, s[76:77], v194, v194, 1.0
	v_div_scale_f32 v203, s[76:77], v195, v195, 1.0
	v_div_scale_f32 v204, s[76:77], v196, v196, 1.0
	v_div_scale_f32 v205, s[76:77], v197, v197, 1.0
	v_div_scale_f32 v206, s[76:77], v198, v198, 1.0
	v_div_scale_f32 v207, s[76:77], v199, v199, 1.0
	v_rcp_f32_e32 v208, v200
	v_rcp_f32_e32 v209, v201
	v_rcp_f32_e32 v210, v202
	v_rcp_f32_e32 v211, v203
	v_rcp_f32_e32 v212, v204
	v_rcp_f32_e32 v213, v205
	v_rcp_f32_e32 v214, v206
	v_rcp_f32_e32 v215, v207
	v_fma_f32 v184, -v200, v208, 1.0
	v_fma_f32 v185, -v201, v209, 1.0
	v_fma_f32 v186, -v202, v210, 1.0
	v_fma_f32 v187, -v203, v211, 1.0
	v_fma_f32 v188, -v204, v212, 1.0
	v_fma_f32 v189, -v205, v213, 1.0
	v_fma_f32 v190, -v206, v214, 1.0
	v_fma_f32 v191, -v207, v215, 1.0
	v_fmac_f32_e32 v208, v184, v208
	v_fmac_f32_e32 v209, v185, v209
	v_fmac_f32_e32 v210, v186, v210
	v_fmac_f32_e32 v211, v187, v211
	v_fmac_f32_e32 v212, v188, v212
	v_fmac_f32_e32 v213, v189, v213
	v_fmac_f32_e32 v214, v190, v214
	v_fmac_f32_e32 v215, v191, v215
	v_div_scale_f32 v216, vcc, 1.0, v192, 1.0
	v_mul_f32_e32 v224, v216, v208
	v_fma_f32 v184, -v200, v224, v216
	v_fmac_f32_e32 v224, v184, v208
	v_fma_f32 v216, -v200, v224, v216
	v_div_fmas_f32 v216, v216, v208, v224
	v_div_fixup_f32 v184, v216, v192, 1.0
	v_div_scale_f32 v217, vcc, 1.0, v193, 1.0
	v_mul_f32_e32 v225, v217, v209
	v_fma_f32 v185, -v201, v225, v217
	v_fmac_f32_e32 v225, v185, v209
	v_fma_f32 v217, -v201, v225, v217
	v_div_fmas_f32 v217, v217, v209, v225
	v_div_fixup_f32 v185, v217, v193, 1.0
	v_div_scale_f32 v218, vcc, 1.0, v194, 1.0
	v_mul_f32_e32 v226, v218, v210
	v_fma_f32 v186, -v202, v226, v218
	v_fmac_f32_e32 v226, v186, v210
	v_fma_f32 v218, -v202, v226, v218
	v_div_fmas_f32 v218, v218, v210, v226
	v_div_fixup_f32 v186, v218, v194, 1.0
	v_div_scale_f32 v219, vcc, 1.0, v195, 1.0
	v_mul_f32_e32 v227, v219, v211
	v_fma_f32 v187, -v203, v227, v219
	v_fmac_f32_e32 v227, v187, v211
	v_fma_f32 v219, -v203, v227, v219
	v_div_fmas_f32 v219, v219, v211, v227
	v_div_fixup_f32 v187, v219, v195, 1.0
	v_div_scale_f32 v220, vcc, 1.0, v196, 1.0
	v_mul_f32_e32 v228, v220, v212
	v_fma_f32 v188, -v204, v228, v220
	v_fmac_f32_e32 v228, v188, v212
	v_fma_f32 v220, -v204, v228, v220
	v_div_fmas_f32 v220, v220, v212, v228
	v_div_fixup_f32 v188, v220, v196, 1.0
	v_div_scale_f32 v221, vcc, 1.0, v197, 1.0
	v_mul_f32_e32 v229, v221, v213
	v_fma_f32 v189, -v205, v229, v221
	v_fmac_f32_e32 v229, v189, v213
	v_fma_f32 v221, -v205, v229, v221
	v_div_fmas_f32 v221, v221, v213, v229
	v_div_fixup_f32 v189, v221, v197, 1.0
	v_div_scale_f32 v222, vcc, 1.0, v198, 1.0
	v_mul_f32_e32 v230, v222, v214
	v_fma_f32 v190, -v206, v230, v222
	v_fmac_f32_e32 v230, v190, v214
	v_fma_f32 v222, -v206, v230, v222
	v_div_fmas_f32 v222, v222, v214, v230
	v_div_fixup_f32 v190, v222, v198, 1.0
	v_div_scale_f32 v223, vcc, 1.0, v199, 1.0
	v_mul_f32_e32 v231, v223, v215
	v_fma_f32 v191, -v207, v231, v223
	v_fmac_f32_e32 v231, v191, v215
	v_fma_f32 v223, -v207, v231, v223
	v_div_fmas_f32 v223, v223, v215, v231
	v_div_fixup_f32 v191, v223, v199, 1.0
	v_lshlrev_b32_e32 v192, 16, v148
	v_and_b32_e32 v193, 0xffff0000, v148
	v_lshlrev_b32_e32 v200, 16, v164
	v_and_b32_e32 v201, 0xffff0000, v164
	v_lshlrev_b32_e32 v194, 16, v149
	v_and_b32_e32 v195, 0xffff0000, v149
	v_lshlrev_b32_e32 v202, 16, v165
	v_and_b32_e32 v203, 0xffff0000, v165
	v_lshlrev_b32_e32 v196, 16, v150
	v_and_b32_e32 v197, 0xffff0000, v150
	v_lshlrev_b32_e32 v204, 16, v166
	v_and_b32_e32 v205, 0xffff0000, v166
	v_lshlrev_b32_e32 v198, 16, v151
	v_and_b32_e32 v199, 0xffff0000, v151
	v_lshlrev_b32_e32 v206, 16, v167
	v_and_b32_e32 v207, 0xffff0000, v167
	v_fma_f32 v184, v184, v200, v192
	v_fma_f32 v185, v185, v201, v193
	v_fma_f32 v186, v186, v202, v194
	v_fma_f32 v187, v187, v203, v195
	v_fma_f32 v188, v188, v204, v196
	v_fma_f32 v189, v189, v205, v197
	v_fma_f32 v190, v190, v206, v198
	v_fma_f32 v191, v191, v207, v199
	v_cvt_pk_bf16_f32 v216, v184, v185
	v_cvt_pk_bf16_f32 v217, v186, v187
	v_cvt_pk_bf16_f32 v218, v188, v189
	v_cvt_pk_bf16_f32 v219, v190, v191
	s_nop 1
	v_permlane16_swap_b32_e32 v216, v218
	v_permlane16_swap_b32_e32 v217, v219
	global_store_dwordx4 v245, v[216:219], s[26:27]
	s_waitcnt vmcnt(5)
	v_add_f32_e32 v184, v8, v136
	v_add_f32_e32 v185, v9, v137
	v_add_f32_e32 v186, v10, v138
	v_add_f32_e32 v187, v11, v139
	v_add_f32_e32 v188, v12, v140
	v_add_f32_e32 v189, v13, v141
	v_add_f32_e32 v190, v14, v142
	v_add_f32_e32 v191, v15, v143
	v_mul_f32_e32 v184, 0xbfb8aa3b, v184
	v_mul_f32_e32 v185, 0xbfb8aa3b, v185
	v_mul_f32_e32 v186, 0xbfb8aa3b, v186
	v_mul_f32_e32 v187, 0xbfb8aa3b, v187
	v_mul_f32_e32 v188, 0xbfb8aa3b, v188
	v_mul_f32_e32 v189, 0xbfb8aa3b, v189
	v_mul_f32_e32 v190, 0xbfb8aa3b, v190
	v_mul_f32_e32 v191, 0xbfb8aa3b, v191
	v_exp_f32_e32 v192, v184
	v_exp_f32_e32 v193, v185
	v_exp_f32_e32 v194, v186
	v_exp_f32_e32 v195, v187
	v_exp_f32_e32 v196, v188
	v_exp_f32_e32 v197, v189
	v_exp_f32_e32 v198, v190
	v_exp_f32_e32 v199, v191
	v_add_f32_e32 v192, 1.0, v192
	v_add_f32_e32 v193, 1.0, v193
	v_add_f32_e32 v194, 1.0, v194
	v_add_f32_e32 v195, 1.0, v195
	v_add_f32_e32 v196, 1.0, v196
	v_add_f32_e32 v197, 1.0, v197
	v_add_f32_e32 v198, 1.0, v198
	v_add_f32_e32 v199, 1.0, v199
	v_div_scale_f32 v200, s[76:77], v192, v192, 1.0
	v_div_scale_f32 v201, s[76:77], v193, v193, 1.0
	v_div_scale_f32 v202, s[76:77], v194, v194, 1.0
	v_div_scale_f32 v203, s[76:77], v195, v195, 1.0
	v_div_scale_f32 v204, s[76:77], v196, v196, 1.0
	v_div_scale_f32 v205, s[76:77], v197, v197, 1.0
	v_div_scale_f32 v206, s[76:77], v198, v198, 1.0
	v_div_scale_f32 v207, s[76:77], v199, v199, 1.0
	v_rcp_f32_e32 v208, v200
	v_rcp_f32_e32 v209, v201
	v_rcp_f32_e32 v210, v202
	v_rcp_f32_e32 v211, v203
	v_rcp_f32_e32 v212, v204
	v_rcp_f32_e32 v213, v205
	v_rcp_f32_e32 v214, v206
	v_rcp_f32_e32 v215, v207
	v_fma_f32 v184, -v200, v208, 1.0
	v_fma_f32 v185, -v201, v209, 1.0
	v_fma_f32 v186, -v202, v210, 1.0
	v_fma_f32 v187, -v203, v211, 1.0
	v_fma_f32 v188, -v204, v212, 1.0
	v_fma_f32 v189, -v205, v213, 1.0
	v_fma_f32 v190, -v206, v214, 1.0
	v_fma_f32 v191, -v207, v215, 1.0
	v_fmac_f32_e32 v208, v184, v208
	v_fmac_f32_e32 v209, v185, v209
	v_fmac_f32_e32 v210, v186, v210
	v_fmac_f32_e32 v211, v187, v211
	v_fmac_f32_e32 v212, v188, v212
	v_fmac_f32_e32 v213, v189, v213
	v_fmac_f32_e32 v214, v190, v214
	v_fmac_f32_e32 v215, v191, v215
	v_div_scale_f32 v216, vcc, 1.0, v192, 1.0
	v_mul_f32_e32 v224, v216, v208
	v_fma_f32 v184, -v200, v224, v216
	v_fmac_f32_e32 v224, v184, v208
	v_fma_f32 v216, -v200, v224, v216
	v_div_fmas_f32 v216, v216, v208, v224
	v_div_fixup_f32 v184, v216, v192, 1.0
	v_div_scale_f32 v217, vcc, 1.0, v193, 1.0
	v_mul_f32_e32 v225, v217, v209
	v_fma_f32 v185, -v201, v225, v217
	v_fmac_f32_e32 v225, v185, v209
	v_fma_f32 v217, -v201, v225, v217
	v_div_fmas_f32 v217, v217, v209, v225
	v_div_fixup_f32 v185, v217, v193, 1.0
	v_div_scale_f32 v218, vcc, 1.0, v194, 1.0
	v_mul_f32_e32 v226, v218, v210
	v_fma_f32 v186, -v202, v226, v218
	v_fmac_f32_e32 v226, v186, v210
	v_fma_f32 v218, -v202, v226, v218
	v_div_fmas_f32 v218, v218, v210, v226
	v_div_fixup_f32 v186, v218, v194, 1.0
	v_div_scale_f32 v219, vcc, 1.0, v195, 1.0
	v_mul_f32_e32 v227, v219, v211
	v_fma_f32 v187, -v203, v227, v219
	v_fmac_f32_e32 v227, v187, v211
	v_fma_f32 v219, -v203, v227, v219
	v_div_fmas_f32 v219, v219, v211, v227
	v_div_fixup_f32 v187, v219, v195, 1.0
	v_div_scale_f32 v220, vcc, 1.0, v196, 1.0
	v_mul_f32_e32 v228, v220, v212
	v_fma_f32 v188, -v204, v228, v220
	v_fmac_f32_e32 v228, v188, v212
	v_fma_f32 v220, -v204, v228, v220
	v_div_fmas_f32 v220, v220, v212, v228
	v_div_fixup_f32 v188, v220, v196, 1.0
	v_div_scale_f32 v221, vcc, 1.0, v197, 1.0
	v_mul_f32_e32 v229, v221, v213
	v_fma_f32 v189, -v205, v229, v221
	v_fmac_f32_e32 v229, v189, v213
	v_fma_f32 v221, -v205, v229, v221
	v_div_fmas_f32 v221, v221, v213, v229
	v_div_fixup_f32 v189, v221, v197, 1.0
	v_div_scale_f32 v222, vcc, 1.0, v198, 1.0
	v_mul_f32_e32 v230, v222, v214
	v_fma_f32 v190, -v206, v230, v222
	v_fmac_f32_e32 v230, v190, v214
	v_fma_f32 v222, -v206, v230, v222
	v_div_fmas_f32 v222, v222, v214, v230
	v_div_fixup_f32 v190, v222, v198, 1.0
	v_div_scale_f32 v223, vcc, 1.0, v199, 1.0
	v_mul_f32_e32 v231, v223, v215
	v_fma_f32 v191, -v207, v231, v223
	v_fmac_f32_e32 v231, v191, v215
	v_fma_f32 v223, -v207, v231, v223
	v_div_fmas_f32 v223, v223, v215, v231
	v_div_fixup_f32 v191, v223, v199, 1.0
	v_lshlrev_b32_e32 v192, 16, v152
	v_and_b32_e32 v193, 0xffff0000, v152
	v_lshlrev_b32_e32 v200, 16, v172
	v_and_b32_e32 v201, 0xffff0000, v172
	v_lshlrev_b32_e32 v194, 16, v153
	v_and_b32_e32 v195, 0xffff0000, v153
	v_lshlrev_b32_e32 v202, 16, v173
	v_and_b32_e32 v203, 0xffff0000, v173
	v_lshlrev_b32_e32 v196, 16, v154
	v_and_b32_e32 v197, 0xffff0000, v154
	v_lshlrev_b32_e32 v204, 16, v174
	v_and_b32_e32 v205, 0xffff0000, v174
	v_lshlrev_b32_e32 v198, 16, v155
	v_and_b32_e32 v199, 0xffff0000, v155
	v_lshlrev_b32_e32 v206, 16, v175
	v_and_b32_e32 v207, 0xffff0000, v175
	v_fma_f32 v184, v184, v200, v192
	v_fma_f32 v185, v185, v201, v193
	v_fma_f32 v186, v186, v202, v194
	v_fma_f32 v187, v187, v203, v195
	v_fma_f32 v188, v188, v204, v196
	v_fma_f32 v189, v189, v205, v197
	v_fma_f32 v190, v190, v206, v198
	v_fma_f32 v191, v191, v207, v199
	v_cvt_pk_bf16_f32 v220, v184, v185
	v_cvt_pk_bf16_f32 v221, v186, v187
	v_cvt_pk_bf16_f32 v222, v188, v189
	v_cvt_pk_bf16_f32 v223, v190, v191
	s_nop 1
	v_permlane16_swap_b32_e32 v220, v222
	v_permlane16_swap_b32_e32 v221, v223
	global_store_dwordx4 v245, v[220:223], s[26:27] offset:64
	s_waitcnt vmcnt(4)
	v_add_f32_e32 v184, v16, v128
	v_add_f32_e32 v185, v17, v129
	v_add_f32_e32 v186, v18, v130
	v_add_f32_e32 v187, v19, v131
	v_add_f32_e32 v188, v20, v132
	v_add_f32_e32 v189, v21, v133
	v_add_f32_e32 v190, v22, v134
	v_add_f32_e32 v191, v23, v135
	v_mul_f32_e32 v184, 0xbfb8aa3b, v184
	v_mul_f32_e32 v185, 0xbfb8aa3b, v185
	v_mul_f32_e32 v186, 0xbfb8aa3b, v186
	v_mul_f32_e32 v187, 0xbfb8aa3b, v187
	v_mul_f32_e32 v188, 0xbfb8aa3b, v188
	v_mul_f32_e32 v189, 0xbfb8aa3b, v189
	v_mul_f32_e32 v190, 0xbfb8aa3b, v190
	v_mul_f32_e32 v191, 0xbfb8aa3b, v191
	v_exp_f32_e32 v192, v184
	v_exp_f32_e32 v193, v185
	v_exp_f32_e32 v194, v186
	v_exp_f32_e32 v195, v187
	v_exp_f32_e32 v196, v188
	v_exp_f32_e32 v197, v189
	v_exp_f32_e32 v198, v190
	v_exp_f32_e32 v199, v191
	v_add_f32_e32 v192, 1.0, v192
	v_add_f32_e32 v193, 1.0, v193
	v_add_f32_e32 v194, 1.0, v194
	v_add_f32_e32 v195, 1.0, v195
	v_add_f32_e32 v196, 1.0, v196
	v_add_f32_e32 v197, 1.0, v197
	v_add_f32_e32 v198, 1.0, v198
	v_add_f32_e32 v199, 1.0, v199
	v_div_scale_f32 v200, s[76:77], v192, v192, 1.0
	v_div_scale_f32 v201, s[76:77], v193, v193, 1.0
	v_div_scale_f32 v202, s[76:77], v194, v194, 1.0
	v_div_scale_f32 v203, s[76:77], v195, v195, 1.0
	v_div_scale_f32 v204, s[76:77], v196, v196, 1.0
	v_div_scale_f32 v205, s[76:77], v197, v197, 1.0
	v_div_scale_f32 v206, s[76:77], v198, v198, 1.0
	v_div_scale_f32 v207, s[76:77], v199, v199, 1.0
	v_rcp_f32_e32 v208, v200
	v_rcp_f32_e32 v209, v201
	v_rcp_f32_e32 v210, v202
	v_rcp_f32_e32 v211, v203
	v_rcp_f32_e32 v212, v204
	v_rcp_f32_e32 v213, v205
	v_rcp_f32_e32 v214, v206
	v_rcp_f32_e32 v215, v207
	v_fma_f32 v184, -v200, v208, 1.0
	v_fma_f32 v185, -v201, v209, 1.0
	v_fma_f32 v186, -v202, v210, 1.0
	v_fma_f32 v187, -v203, v211, 1.0
	v_fma_f32 v188, -v204, v212, 1.0
	v_fma_f32 v189, -v205, v213, 1.0
	v_fma_f32 v190, -v206, v214, 1.0
	v_fma_f32 v191, -v207, v215, 1.0
	v_fmac_f32_e32 v208, v184, v208
	v_fmac_f32_e32 v209, v185, v209
	v_fmac_f32_e32 v210, v186, v210
	v_fmac_f32_e32 v211, v187, v211
	v_fmac_f32_e32 v212, v188, v212
	v_fmac_f32_e32 v213, v189, v213
	v_fmac_f32_e32 v214, v190, v214
	v_fmac_f32_e32 v215, v191, v215
	v_div_scale_f32 v216, vcc, 1.0, v192, 1.0
	v_mul_f32_e32 v224, v216, v208
	v_fma_f32 v184, -v200, v224, v216
	v_fmac_f32_e32 v224, v184, v208
	v_fma_f32 v216, -v200, v224, v216
	v_div_fmas_f32 v216, v216, v208, v224
	v_div_fixup_f32 v184, v216, v192, 1.0
	v_div_scale_f32 v217, vcc, 1.0, v193, 1.0
	v_mul_f32_e32 v225, v217, v209
	v_fma_f32 v185, -v201, v225, v217
	v_fmac_f32_e32 v225, v185, v209
	v_fma_f32 v217, -v201, v225, v217
	v_div_fmas_f32 v217, v217, v209, v225
	v_div_fixup_f32 v185, v217, v193, 1.0
	v_div_scale_f32 v218, vcc, 1.0, v194, 1.0
	v_mul_f32_e32 v226, v218, v210
	v_fma_f32 v186, -v202, v226, v218
	v_fmac_f32_e32 v226, v186, v210
	v_fma_f32 v218, -v202, v226, v218
	v_div_fmas_f32 v218, v218, v210, v226
	v_div_fixup_f32 v186, v218, v194, 1.0
	v_div_scale_f32 v219, vcc, 1.0, v195, 1.0
	v_mul_f32_e32 v227, v219, v211
	v_fma_f32 v187, -v203, v227, v219
	v_fmac_f32_e32 v227, v187, v211
	v_fma_f32 v219, -v203, v227, v219
	v_div_fmas_f32 v219, v219, v211, v227
	v_div_fixup_f32 v187, v219, v195, 1.0
	v_div_scale_f32 v220, vcc, 1.0, v196, 1.0
	v_mul_f32_e32 v228, v220, v212
	v_fma_f32 v188, -v204, v228, v220
	v_fmac_f32_e32 v228, v188, v212
	v_fma_f32 v220, -v204, v228, v220
	v_div_fmas_f32 v220, v220, v212, v228
	v_div_fixup_f32 v188, v220, v196, 1.0
	v_div_scale_f32 v221, vcc, 1.0, v197, 1.0
	v_mul_f32_e32 v229, v221, v213
	v_fma_f32 v189, -v205, v229, v221
	v_fmac_f32_e32 v229, v189, v213
	v_fma_f32 v221, -v205, v229, v221
	v_div_fmas_f32 v221, v221, v213, v229
	v_div_fixup_f32 v189, v221, v197, 1.0
	v_div_scale_f32 v222, vcc, 1.0, v198, 1.0
	v_mul_f32_e32 v230, v222, v214
	v_fma_f32 v190, -v206, v230, v222
	v_fmac_f32_e32 v230, v190, v214
	v_fma_f32 v222, -v206, v230, v222
	v_div_fmas_f32 v222, v222, v214, v230
	v_div_fixup_f32 v190, v222, v198, 1.0
	v_div_scale_f32 v223, vcc, 1.0, v199, 1.0
	v_mul_f32_e32 v231, v223, v215
	v_fma_f32 v191, -v207, v231, v223
	v_fmac_f32_e32 v231, v191, v215
	v_fma_f32 v223, -v207, v231, v223
	v_div_fmas_f32 v223, v223, v215, v231
	v_div_fixup_f32 v191, v223, v199, 1.0
	v_lshlrev_b32_e32 v192, 16, v156
	v_and_b32_e32 v193, 0xffff0000, v156
	v_lshlrev_b32_e32 v200, 16, v176
	v_and_b32_e32 v201, 0xffff0000, v176
	v_lshlrev_b32_e32 v194, 16, v157
	v_and_b32_e32 v195, 0xffff0000, v157
	v_lshlrev_b32_e32 v202, 16, v177
	v_and_b32_e32 v203, 0xffff0000, v177
	v_lshlrev_b32_e32 v196, 16, v158
	v_and_b32_e32 v197, 0xffff0000, v158
	v_lshlrev_b32_e32 v204, 16, v178
	v_and_b32_e32 v205, 0xffff0000, v178
	v_lshlrev_b32_e32 v198, 16, v159
	v_and_b32_e32 v199, 0xffff0000, v159
	v_lshlrev_b32_e32 v206, 16, v179
	v_and_b32_e32 v207, 0xffff0000, v179
	v_fma_f32 v184, v184, v200, v192
	v_fma_f32 v185, v185, v201, v193
	v_fma_f32 v186, v186, v202, v194
	v_fma_f32 v187, v187, v203, v195
	v_fma_f32 v188, v188, v204, v196
	v_fma_f32 v189, v189, v205, v197
	v_fma_f32 v190, v190, v206, v198
	v_fma_f32 v191, v191, v207, v199
	v_cvt_pk_bf16_f32 v216, v184, v185
	v_cvt_pk_bf16_f32 v217, v186, v187
	v_cvt_pk_bf16_f32 v218, v188, v189
	v_cvt_pk_bf16_f32 v219, v190, v191
	s_nop 1
	v_permlane16_swap_b32_e32 v216, v218
	v_permlane16_swap_b32_e32 v217, v219
	global_store_dwordx4 v246, v[216:219], s[26:27]
	s_waitcnt vmcnt(3)
	v_add_f32_e32 v184, v24, v136
	v_add_f32_e32 v185, v25, v137
	v_add_f32_e32 v186, v26, v138
	v_add_f32_e32 v187, v27, v139
	v_add_f32_e32 v188, v28, v140
	v_add_f32_e32 v189, v29, v141
	v_add_f32_e32 v190, v30, v142
	v_add_f32_e32 v191, v31, v143
	v_mul_f32_e32 v184, 0xbfb8aa3b, v184
	v_mul_f32_e32 v185, 0xbfb8aa3b, v185
	v_mul_f32_e32 v186, 0xbfb8aa3b, v186
	v_mul_f32_e32 v187, 0xbfb8aa3b, v187
	v_mul_f32_e32 v188, 0xbfb8aa3b, v188
	v_mul_f32_e32 v189, 0xbfb8aa3b, v189
	v_mul_f32_e32 v190, 0xbfb8aa3b, v190
	v_mul_f32_e32 v191, 0xbfb8aa3b, v191
	v_exp_f32_e32 v192, v184
	v_exp_f32_e32 v193, v185
	v_exp_f32_e32 v194, v186
	v_exp_f32_e32 v195, v187
	v_exp_f32_e32 v196, v188
	v_exp_f32_e32 v197, v189
	v_exp_f32_e32 v198, v190
	v_exp_f32_e32 v199, v191
	v_add_f32_e32 v192, 1.0, v192
	v_add_f32_e32 v193, 1.0, v193
	v_add_f32_e32 v194, 1.0, v194
	v_add_f32_e32 v195, 1.0, v195
	v_add_f32_e32 v196, 1.0, v196
	v_add_f32_e32 v197, 1.0, v197
	v_add_f32_e32 v198, 1.0, v198
	v_add_f32_e32 v199, 1.0, v199
	v_div_scale_f32 v200, s[76:77], v192, v192, 1.0
	v_div_scale_f32 v201, s[76:77], v193, v193, 1.0
	v_div_scale_f32 v202, s[76:77], v194, v194, 1.0
	v_div_scale_f32 v203, s[76:77], v195, v195, 1.0
	v_div_scale_f32 v204, s[76:77], v196, v196, 1.0
	v_div_scale_f32 v205, s[76:77], v197, v197, 1.0
	v_div_scale_f32 v206, s[76:77], v198, v198, 1.0
	v_div_scale_f32 v207, s[76:77], v199, v199, 1.0
	v_rcp_f32_e32 v208, v200
	v_rcp_f32_e32 v209, v201
	v_rcp_f32_e32 v210, v202
	v_rcp_f32_e32 v211, v203
	v_rcp_f32_e32 v212, v204
	v_rcp_f32_e32 v213, v205
	v_rcp_f32_e32 v214, v206
	v_rcp_f32_e32 v215, v207
	v_fma_f32 v184, -v200, v208, 1.0
	v_fma_f32 v185, -v201, v209, 1.0
	v_fma_f32 v186, -v202, v210, 1.0
	v_fma_f32 v187, -v203, v211, 1.0
	v_fma_f32 v188, -v204, v212, 1.0
	v_fma_f32 v189, -v205, v213, 1.0
	v_fma_f32 v190, -v206, v214, 1.0
	v_fma_f32 v191, -v207, v215, 1.0
	v_fmac_f32_e32 v208, v184, v208
	v_fmac_f32_e32 v209, v185, v209
	v_fmac_f32_e32 v210, v186, v210
	v_fmac_f32_e32 v211, v187, v211
	v_fmac_f32_e32 v212, v188, v212
	v_fmac_f32_e32 v213, v189, v213
	v_fmac_f32_e32 v214, v190, v214
	v_fmac_f32_e32 v215, v191, v215
	v_div_scale_f32 v216, vcc, 1.0, v192, 1.0
	v_mul_f32_e32 v224, v216, v208
	v_fma_f32 v184, -v200, v224, v216
	v_fmac_f32_e32 v224, v184, v208
	v_fma_f32 v216, -v200, v224, v216
	v_div_fmas_f32 v216, v216, v208, v224
	v_div_fixup_f32 v184, v216, v192, 1.0
	v_div_scale_f32 v217, vcc, 1.0, v193, 1.0
	v_mul_f32_e32 v225, v217, v209
	v_fma_f32 v185, -v201, v225, v217
	v_fmac_f32_e32 v225, v185, v209
	v_fma_f32 v217, -v201, v225, v217
	v_div_fmas_f32 v217, v217, v209, v225
	v_div_fixup_f32 v185, v217, v193, 1.0
	v_div_scale_f32 v218, vcc, 1.0, v194, 1.0
	v_mul_f32_e32 v226, v218, v210
	v_fma_f32 v186, -v202, v226, v218
	v_fmac_f32_e32 v226, v186, v210
	v_fma_f32 v218, -v202, v226, v218
	v_div_fmas_f32 v218, v218, v210, v226
	v_div_fixup_f32 v186, v218, v194, 1.0
	v_div_scale_f32 v219, vcc, 1.0, v195, 1.0
	v_mul_f32_e32 v227, v219, v211
	v_fma_f32 v187, -v203, v227, v219
	v_fmac_f32_e32 v227, v187, v211
	v_fma_f32 v219, -v203, v227, v219
	v_div_fmas_f32 v219, v219, v211, v227
	v_div_fixup_f32 v187, v219, v195, 1.0
	v_div_scale_f32 v220, vcc, 1.0, v196, 1.0
	v_mul_f32_e32 v228, v220, v212
	v_fma_f32 v188, -v204, v228, v220
	v_fmac_f32_e32 v228, v188, v212
	v_fma_f32 v220, -v204, v228, v220
	v_div_fmas_f32 v220, v220, v212, v228
	v_div_fixup_f32 v188, v220, v196, 1.0
	v_div_scale_f32 v221, vcc, 1.0, v197, 1.0
	v_mul_f32_e32 v229, v221, v213
	v_fma_f32 v189, -v205, v229, v221
	v_fmac_f32_e32 v229, v189, v213
	v_fma_f32 v221, -v205, v229, v221
	v_div_fmas_f32 v221, v221, v213, v229
	v_div_fixup_f32 v189, v221, v197, 1.0
	v_div_scale_f32 v222, vcc, 1.0, v198, 1.0
	v_mul_f32_e32 v230, v222, v214
	v_fma_f32 v190, -v206, v230, v222
	v_fmac_f32_e32 v230, v190, v214
	v_fma_f32 v222, -v206, v230, v222
	v_div_fmas_f32 v222, v222, v214, v230
	v_div_fixup_f32 v190, v222, v198, 1.0
	v_div_scale_f32 v223, vcc, 1.0, v199, 1.0
	v_mul_f32_e32 v231, v223, v215
	v_fma_f32 v191, -v207, v231, v223
	v_fmac_f32_e32 v231, v191, v215
	v_fma_f32 v223, -v207, v231, v223
	v_div_fmas_f32 v223, v223, v215, v231
	v_div_fixup_f32 v191, v223, v199, 1.0
	v_lshlrev_b32_e32 v192, 16, v160
	v_and_b32_e32 v193, 0xffff0000, v160
	v_lshlrev_b32_e32 v200, 16, v180
	v_and_b32_e32 v201, 0xffff0000, v180
	v_lshlrev_b32_e32 v194, 16, v161
	v_and_b32_e32 v195, 0xffff0000, v161
	v_lshlrev_b32_e32 v202, 16, v181
	v_and_b32_e32 v203, 0xffff0000, v181
	v_lshlrev_b32_e32 v196, 16, v162
	v_and_b32_e32 v197, 0xffff0000, v162
	v_lshlrev_b32_e32 v204, 16, v182
	v_and_b32_e32 v205, 0xffff0000, v182
	v_lshlrev_b32_e32 v198, 16, v163
	v_and_b32_e32 v199, 0xffff0000, v163
	v_lshlrev_b32_e32 v206, 16, v183
	v_and_b32_e32 v207, 0xffff0000, v183
	v_fma_f32 v184, v184, v200, v192
	v_fma_f32 v185, v185, v201, v193
	v_fma_f32 v186, v186, v202, v194
	v_fma_f32 v187, v187, v203, v195
	v_fma_f32 v188, v188, v204, v196
	v_fma_f32 v189, v189, v205, v197
	v_fma_f32 v190, v190, v206, v198
	v_fma_f32 v191, v191, v207, v199
	v_cvt_pk_bf16_f32 v220, v184, v185
	v_cvt_pk_bf16_f32 v221, v186, v187
	v_cvt_pk_bf16_f32 v222, v188, v189
	v_cvt_pk_bf16_f32 v223, v190, v191
	s_nop 1
	v_permlane16_swap_b32_e32 v220, v222
	v_permlane16_swap_b32_e32 v221, v223
	global_store_dwordx4 v246, v[220:223], s[26:27] offset:64
	global_load_dwordx4 v[148:151], v243, s[86:87]
	s_add_u32 s86, s86, 0x1000
	s_addc_u32 s87, s87, 0
	global_load_dwordx4 v[164:167], v243, s[88:89]
	s_add_u32 s88, s88, 0x1000
	s_addc_u32 s89, s89, 0
	global_load_dwordx4 v[152:155], v243, s[86:87]
	s_add_u32 s86, s86, 0x1000
	s_addc_u32 s87, s87, 0
	global_load_dwordx4 v[172:175], v243, s[88:89]
	s_add_u32 s88, s88, 0x1000
	s_addc_u32 s89, s89, 0
	global_load_dwordx4 v[156:159], v243, s[86:87]
	s_add_u32 s86, s86, 0x1000
	s_addc_u32 s87, s87, 0
	global_load_dwordx4 v[176:179], v243, s[88:89]
	s_add_u32 s88, s88, 0x1000
	s_addc_u32 s89, s89, 0
	global_load_dwordx4 v[160:163], v243, s[86:87]
	s_add_u32 s86, s86, 0x1000
	s_addc_u32 s87, s87, 0
	global_load_dwordx4 v[180:183], v243, s[88:89]
	s_add_u32 s88, s88, 0x1000
	s_addc_u32 s89, s89, 0
	s_waitcnt vmcnt(6)
	v_add_f32_e32 v184, v32, v128
	v_add_f32_e32 v185, v33, v129
	v_add_f32_e32 v186, v34, v130
	v_add_f32_e32 v187, v35, v131
	v_add_f32_e32 v188, v36, v132
	v_add_f32_e32 v189, v37, v133
	v_add_f32_e32 v190, v38, v134
	v_add_f32_e32 v191, v39, v135
	v_mul_f32_e32 v184, 0xbfb8aa3b, v184
	v_mul_f32_e32 v185, 0xbfb8aa3b, v185
	v_mul_f32_e32 v186, 0xbfb8aa3b, v186
	v_mul_f32_e32 v187, 0xbfb8aa3b, v187
	v_mul_f32_e32 v188, 0xbfb8aa3b, v188
	v_mul_f32_e32 v189, 0xbfb8aa3b, v189
	v_mul_f32_e32 v190, 0xbfb8aa3b, v190
	v_mul_f32_e32 v191, 0xbfb8aa3b, v191
	v_exp_f32_e32 v192, v184
	v_exp_f32_e32 v193, v185
	v_exp_f32_e32 v194, v186
	v_exp_f32_e32 v195, v187
	v_exp_f32_e32 v196, v188
	v_exp_f32_e32 v197, v189
	v_exp_f32_e32 v198, v190
	v_exp_f32_e32 v199, v191
	v_add_f32_e32 v192, 1.0, v192
	v_add_f32_e32 v193, 1.0, v193
	v_add_f32_e32 v194, 1.0, v194
	v_add_f32_e32 v195, 1.0, v195
	v_add_f32_e32 v196, 1.0, v196
	v_add_f32_e32 v197, 1.0, v197
	v_add_f32_e32 v198, 1.0, v198
	v_add_f32_e32 v199, 1.0, v199
	v_div_scale_f32 v200, s[76:77], v192, v192, 1.0
	v_div_scale_f32 v201, s[76:77], v193, v193, 1.0
	v_div_scale_f32 v202, s[76:77], v194, v194, 1.0
	v_div_scale_f32 v203, s[76:77], v195, v195, 1.0
	v_div_scale_f32 v204, s[76:77], v196, v196, 1.0
	v_div_scale_f32 v205, s[76:77], v197, v197, 1.0
	v_div_scale_f32 v206, s[76:77], v198, v198, 1.0
	v_div_scale_f32 v207, s[76:77], v199, v199, 1.0
	v_rcp_f32_e32 v208, v200
	v_rcp_f32_e32 v209, v201
	v_rcp_f32_e32 v210, v202
	v_rcp_f32_e32 v211, v203
	v_rcp_f32_e32 v212, v204
	v_rcp_f32_e32 v213, v205
	v_rcp_f32_e32 v214, v206
	v_rcp_f32_e32 v215, v207
	v_fma_f32 v184, -v200, v208, 1.0
	v_fma_f32 v185, -v201, v209, 1.0
	v_fma_f32 v186, -v202, v210, 1.0
	v_fma_f32 v187, -v203, v211, 1.0
	v_fma_f32 v188, -v204, v212, 1.0
	v_fma_f32 v189, -v205, v213, 1.0
	v_fma_f32 v190, -v206, v214, 1.0
	v_fma_f32 v191, -v207, v215, 1.0
	v_fmac_f32_e32 v208, v184, v208
	v_fmac_f32_e32 v209, v185, v209
	v_fmac_f32_e32 v210, v186, v210
	v_fmac_f32_e32 v211, v187, v211
	v_fmac_f32_e32 v212, v188, v212
	v_fmac_f32_e32 v213, v189, v213
	v_fmac_f32_e32 v214, v190, v214
	v_fmac_f32_e32 v215, v191, v215
	v_div_scale_f32 v216, vcc, 1.0, v192, 1.0
	v_mul_f32_e32 v224, v216, v208
	v_fma_f32 v184, -v200, v224, v216
	v_fmac_f32_e32 v224, v184, v208
	v_fma_f32 v216, -v200, v224, v216
	v_div_fmas_f32 v216, v216, v208, v224
	v_div_fixup_f32 v184, v216, v192, 1.0
	v_div_scale_f32 v217, vcc, 1.0, v193, 1.0
	v_mul_f32_e32 v225, v217, v209
	v_fma_f32 v185, -v201, v225, v217
	v_fmac_f32_e32 v225, v185, v209
	v_fma_f32 v217, -v201, v225, v217
	v_div_fmas_f32 v217, v217, v209, v225
	v_div_fixup_f32 v185, v217, v193, 1.0
	v_div_scale_f32 v218, vcc, 1.0, v194, 1.0
	v_mul_f32_e32 v226, v218, v210
	v_fma_f32 v186, -v202, v226, v218
	v_fmac_f32_e32 v226, v186, v210
	v_fma_f32 v218, -v202, v226, v218
	v_div_fmas_f32 v218, v218, v210, v226
	v_div_fixup_f32 v186, v218, v194, 1.0
	v_div_scale_f32 v219, vcc, 1.0, v195, 1.0
	v_mul_f32_e32 v227, v219, v211
	v_fma_f32 v187, -v203, v227, v219
	v_fmac_f32_e32 v227, v187, v211
	v_fma_f32 v219, -v203, v227, v219
	v_div_fmas_f32 v219, v219, v211, v227
	v_div_fixup_f32 v187, v219, v195, 1.0
	v_div_scale_f32 v220, vcc, 1.0, v196, 1.0
	v_mul_f32_e32 v228, v220, v212
	v_fma_f32 v188, -v204, v228, v220
	v_fmac_f32_e32 v228, v188, v212
	v_fma_f32 v220, -v204, v228, v220
	v_div_fmas_f32 v220, v220, v212, v228
	v_div_fixup_f32 v188, v220, v196, 1.0
	v_div_scale_f32 v221, vcc, 1.0, v197, 1.0
	v_mul_f32_e32 v229, v221, v213
	v_fma_f32 v189, -v205, v229, v221
	v_fmac_f32_e32 v229, v189, v213
	v_fma_f32 v221, -v205, v229, v221
	v_div_fmas_f32 v221, v221, v213, v229
	v_div_fixup_f32 v189, v221, v197, 1.0
	v_div_scale_f32 v222, vcc, 1.0, v198, 1.0
	v_mul_f32_e32 v230, v222, v214
	v_fma_f32 v190, -v206, v230, v222
	v_fmac_f32_e32 v230, v190, v214
	v_fma_f32 v222, -v206, v230, v222
	v_div_fmas_f32 v222, v222, v214, v230
	v_div_fixup_f32 v190, v222, v198, 1.0
	v_div_scale_f32 v223, vcc, 1.0, v199, 1.0
	v_mul_f32_e32 v231, v223, v215
	v_fma_f32 v191, -v207, v231, v223
	v_fmac_f32_e32 v231, v191, v215
	v_fma_f32 v223, -v207, v231, v223
	v_div_fmas_f32 v223, v223, v215, v231
	v_div_fixup_f32 v191, v223, v199, 1.0
	v_lshlrev_b32_e32 v192, 16, v148
	v_and_b32_e32 v193, 0xffff0000, v148
	v_lshlrev_b32_e32 v200, 16, v164
	v_and_b32_e32 v201, 0xffff0000, v164
	v_lshlrev_b32_e32 v194, 16, v149
	v_and_b32_e32 v195, 0xffff0000, v149
	v_lshlrev_b32_e32 v202, 16, v165
	v_and_b32_e32 v203, 0xffff0000, v165
	v_lshlrev_b32_e32 v196, 16, v150
	v_and_b32_e32 v197, 0xffff0000, v150
	v_lshlrev_b32_e32 v204, 16, v166
	v_and_b32_e32 v205, 0xffff0000, v166
	v_lshlrev_b32_e32 v198, 16, v151
	v_and_b32_e32 v199, 0xffff0000, v151
	v_lshlrev_b32_e32 v206, 16, v167
	v_and_b32_e32 v207, 0xffff0000, v167
	v_fma_f32 v184, v184, v200, v192
	v_fma_f32 v185, v185, v201, v193
	v_fma_f32 v186, v186, v202, v194
	v_fma_f32 v187, v187, v203, v195
	v_fma_f32 v188, v188, v204, v196
	v_fma_f32 v189, v189, v205, v197
	v_fma_f32 v190, v190, v206, v198
	v_fma_f32 v191, v191, v207, v199
	v_cvt_pk_bf16_f32 v216, v184, v185
	v_cvt_pk_bf16_f32 v217, v186, v187
	v_cvt_pk_bf16_f32 v218, v188, v189
	v_cvt_pk_bf16_f32 v219, v190, v191
	s_nop 1
	v_permlane16_swap_b32_e32 v216, v218
	v_permlane16_swap_b32_e32 v217, v219
	global_store_dwordx4 v247, v[216:219], s[26:27]
	s_waitcnt vmcnt(5)
	v_add_f32_e32 v184, v40, v136
	v_add_f32_e32 v185, v41, v137
	v_add_f32_e32 v186, v42, v138
	v_add_f32_e32 v187, v43, v139
	v_add_f32_e32 v188, v44, v140
	v_add_f32_e32 v189, v45, v141
	v_add_f32_e32 v190, v46, v142
	v_add_f32_e32 v191, v47, v143
	v_mul_f32_e32 v184, 0xbfb8aa3b, v184
	v_mul_f32_e32 v185, 0xbfb8aa3b, v185
	v_mul_f32_e32 v186, 0xbfb8aa3b, v186
	v_mul_f32_e32 v187, 0xbfb8aa3b, v187
	v_mul_f32_e32 v188, 0xbfb8aa3b, v188
	v_mul_f32_e32 v189, 0xbfb8aa3b, v189
	v_mul_f32_e32 v190, 0xbfb8aa3b, v190
	v_mul_f32_e32 v191, 0xbfb8aa3b, v191
	v_exp_f32_e32 v192, v184
	v_exp_f32_e32 v193, v185
	v_exp_f32_e32 v194, v186
	v_exp_f32_e32 v195, v187
	v_exp_f32_e32 v196, v188
	v_exp_f32_e32 v197, v189
	v_exp_f32_e32 v198, v190
	v_exp_f32_e32 v199, v191
	v_add_f32_e32 v192, 1.0, v192
	v_add_f32_e32 v193, 1.0, v193
	v_add_f32_e32 v194, 1.0, v194
	v_add_f32_e32 v195, 1.0, v195
	v_add_f32_e32 v196, 1.0, v196
	v_add_f32_e32 v197, 1.0, v197
	v_add_f32_e32 v198, 1.0, v198
	v_add_f32_e32 v199, 1.0, v199
	v_div_scale_f32 v200, s[76:77], v192, v192, 1.0
	v_div_scale_f32 v201, s[76:77], v193, v193, 1.0
	v_div_scale_f32 v202, s[76:77], v194, v194, 1.0
	v_div_scale_f32 v203, s[76:77], v195, v195, 1.0
	v_div_scale_f32 v204, s[76:77], v196, v196, 1.0
	v_div_scale_f32 v205, s[76:77], v197, v197, 1.0
	v_div_scale_f32 v206, s[76:77], v198, v198, 1.0
	v_div_scale_f32 v207, s[76:77], v199, v199, 1.0
	v_rcp_f32_e32 v208, v200
	v_rcp_f32_e32 v209, v201
	v_rcp_f32_e32 v210, v202
	v_rcp_f32_e32 v211, v203
	v_rcp_f32_e32 v212, v204
	v_rcp_f32_e32 v213, v205
	v_rcp_f32_e32 v214, v206
	v_rcp_f32_e32 v215, v207
	v_fma_f32 v184, -v200, v208, 1.0
	v_fma_f32 v185, -v201, v209, 1.0
	v_fma_f32 v186, -v202, v210, 1.0
	v_fma_f32 v187, -v203, v211, 1.0
	v_fma_f32 v188, -v204, v212, 1.0
	v_fma_f32 v189, -v205, v213, 1.0
	v_fma_f32 v190, -v206, v214, 1.0
	v_fma_f32 v191, -v207, v215, 1.0
	v_fmac_f32_e32 v208, v184, v208
	v_fmac_f32_e32 v209, v185, v209
	v_fmac_f32_e32 v210, v186, v210
	v_fmac_f32_e32 v211, v187, v211
	v_fmac_f32_e32 v212, v188, v212
	v_fmac_f32_e32 v213, v189, v213
	v_fmac_f32_e32 v214, v190, v214
	v_fmac_f32_e32 v215, v191, v215
	v_div_scale_f32 v216, vcc, 1.0, v192, 1.0
	v_mul_f32_e32 v224, v216, v208
	v_fma_f32 v184, -v200, v224, v216
	v_fmac_f32_e32 v224, v184, v208
	v_fma_f32 v216, -v200, v224, v216
	v_div_fmas_f32 v216, v216, v208, v224
	v_div_fixup_f32 v184, v216, v192, 1.0
	v_div_scale_f32 v217, vcc, 1.0, v193, 1.0
	v_mul_f32_e32 v225, v217, v209
	v_fma_f32 v185, -v201, v225, v217
	v_fmac_f32_e32 v225, v185, v209
	v_fma_f32 v217, -v201, v225, v217
	v_div_fmas_f32 v217, v217, v209, v225
	v_div_fixup_f32 v185, v217, v193, 1.0
	v_div_scale_f32 v218, vcc, 1.0, v194, 1.0
	v_mul_f32_e32 v226, v218, v210
	v_fma_f32 v186, -v202, v226, v218
	v_fmac_f32_e32 v226, v186, v210
	v_fma_f32 v218, -v202, v226, v218
	v_div_fmas_f32 v218, v218, v210, v226
	v_div_fixup_f32 v186, v218, v194, 1.0
	v_div_scale_f32 v219, vcc, 1.0, v195, 1.0
	v_mul_f32_e32 v227, v219, v211
	v_fma_f32 v187, -v203, v227, v219
	v_fmac_f32_e32 v227, v187, v211
	v_fma_f32 v219, -v203, v227, v219
	v_div_fmas_f32 v219, v219, v211, v227
	v_div_fixup_f32 v187, v219, v195, 1.0
	v_div_scale_f32 v220, vcc, 1.0, v196, 1.0
	v_mul_f32_e32 v228, v220, v212
	v_fma_f32 v188, -v204, v228, v220
	v_fmac_f32_e32 v228, v188, v212
	v_fma_f32 v220, -v204, v228, v220
	v_div_fmas_f32 v220, v220, v212, v228
	v_div_fixup_f32 v188, v220, v196, 1.0
	v_div_scale_f32 v221, vcc, 1.0, v197, 1.0
	v_mul_f32_e32 v229, v221, v213
	v_fma_f32 v189, -v205, v229, v221
	v_fmac_f32_e32 v229, v189, v213
	v_fma_f32 v221, -v205, v229, v221
	v_div_fmas_f32 v221, v221, v213, v229
	v_div_fixup_f32 v189, v221, v197, 1.0
	v_div_scale_f32 v222, vcc, 1.0, v198, 1.0
	v_mul_f32_e32 v230, v222, v214
	v_fma_f32 v190, -v206, v230, v222
	v_fmac_f32_e32 v230, v190, v214
	v_fma_f32 v222, -v206, v230, v222
	v_div_fmas_f32 v222, v222, v214, v230
	v_div_fixup_f32 v190, v222, v198, 1.0
	v_div_scale_f32 v223, vcc, 1.0, v199, 1.0
	v_mul_f32_e32 v231, v223, v215
	v_fma_f32 v191, -v207, v231, v223
	v_fmac_f32_e32 v231, v191, v215
	v_fma_f32 v223, -v207, v231, v223
	v_div_fmas_f32 v223, v223, v215, v231
	v_div_fixup_f32 v191, v223, v199, 1.0
	v_lshlrev_b32_e32 v192, 16, v152
	v_and_b32_e32 v193, 0xffff0000, v152
	v_lshlrev_b32_e32 v200, 16, v172
	v_and_b32_e32 v201, 0xffff0000, v172
	v_lshlrev_b32_e32 v194, 16, v153
	v_and_b32_e32 v195, 0xffff0000, v153
	v_lshlrev_b32_e32 v202, 16, v173
	v_and_b32_e32 v203, 0xffff0000, v173
	v_lshlrev_b32_e32 v196, 16, v154
	v_and_b32_e32 v197, 0xffff0000, v154
	v_lshlrev_b32_e32 v204, 16, v174
	v_and_b32_e32 v205, 0xffff0000, v174
	v_lshlrev_b32_e32 v198, 16, v155
	v_and_b32_e32 v199, 0xffff0000, v155
	v_lshlrev_b32_e32 v206, 16, v175
	v_and_b32_e32 v207, 0xffff0000, v175
	v_fma_f32 v184, v184, v200, v192
	v_fma_f32 v185, v185, v201, v193
	v_fma_f32 v186, v186, v202, v194
	v_fma_f32 v187, v187, v203, v195
	v_fma_f32 v188, v188, v204, v196
	v_fma_f32 v189, v189, v205, v197
	v_fma_f32 v190, v190, v206, v198
	v_fma_f32 v191, v191, v207, v199
	v_cvt_pk_bf16_f32 v220, v184, v185
	v_cvt_pk_bf16_f32 v221, v186, v187
	v_cvt_pk_bf16_f32 v222, v188, v189
	v_cvt_pk_bf16_f32 v223, v190, v191
	s_nop 1
	v_permlane16_swap_b32_e32 v220, v222
	v_permlane16_swap_b32_e32 v221, v223
	global_store_dwordx4 v247, v[220:223], s[26:27] offset:64
	s_waitcnt vmcnt(4)
	v_add_f32_e32 v184, v48, v128
	v_add_f32_e32 v185, v49, v129
	v_add_f32_e32 v186, v50, v130
	v_add_f32_e32 v187, v51, v131
	v_add_f32_e32 v188, v52, v132
	v_add_f32_e32 v189, v53, v133
	v_add_f32_e32 v190, v54, v134
	v_add_f32_e32 v191, v55, v135
	v_mul_f32_e32 v184, 0xbfb8aa3b, v184
	v_mul_f32_e32 v185, 0xbfb8aa3b, v185
	v_mul_f32_e32 v186, 0xbfb8aa3b, v186
	v_mul_f32_e32 v187, 0xbfb8aa3b, v187
	v_mul_f32_e32 v188, 0xbfb8aa3b, v188
	v_mul_f32_e32 v189, 0xbfb8aa3b, v189
	v_mul_f32_e32 v190, 0xbfb8aa3b, v190
	v_mul_f32_e32 v191, 0xbfb8aa3b, v191
	v_exp_f32_e32 v192, v184
	v_exp_f32_e32 v193, v185
	v_exp_f32_e32 v194, v186
	v_exp_f32_e32 v195, v187
	v_exp_f32_e32 v196, v188
	v_exp_f32_e32 v197, v189
	v_exp_f32_e32 v198, v190
	v_exp_f32_e32 v199, v191
	v_add_f32_e32 v192, 1.0, v192
	v_add_f32_e32 v193, 1.0, v193
	v_add_f32_e32 v194, 1.0, v194
	v_add_f32_e32 v195, 1.0, v195
	v_add_f32_e32 v196, 1.0, v196
	v_add_f32_e32 v197, 1.0, v197
	v_add_f32_e32 v198, 1.0, v198
	v_add_f32_e32 v199, 1.0, v199
	v_div_scale_f32 v200, s[76:77], v192, v192, 1.0
	v_div_scale_f32 v201, s[76:77], v193, v193, 1.0
	v_div_scale_f32 v202, s[76:77], v194, v194, 1.0
	v_div_scale_f32 v203, s[76:77], v195, v195, 1.0
	v_div_scale_f32 v204, s[76:77], v196, v196, 1.0
	v_div_scale_f32 v205, s[76:77], v197, v197, 1.0
	v_div_scale_f32 v206, s[76:77], v198, v198, 1.0
	v_div_scale_f32 v207, s[76:77], v199, v199, 1.0
	v_rcp_f32_e32 v208, v200
	v_rcp_f32_e32 v209, v201
	v_rcp_f32_e32 v210, v202
	v_rcp_f32_e32 v211, v203
	v_rcp_f32_e32 v212, v204
	v_rcp_f32_e32 v213, v205
	v_rcp_f32_e32 v214, v206
	v_rcp_f32_e32 v215, v207
	v_fma_f32 v184, -v200, v208, 1.0
	v_fma_f32 v185, -v201, v209, 1.0
	v_fma_f32 v186, -v202, v210, 1.0
	v_fma_f32 v187, -v203, v211, 1.0
	v_fma_f32 v188, -v204, v212, 1.0
	v_fma_f32 v189, -v205, v213, 1.0
	v_fma_f32 v190, -v206, v214, 1.0
	v_fma_f32 v191, -v207, v215, 1.0
	v_fmac_f32_e32 v208, v184, v208
	v_fmac_f32_e32 v209, v185, v209
	v_fmac_f32_e32 v210, v186, v210
	v_fmac_f32_e32 v211, v187, v211
	v_fmac_f32_e32 v212, v188, v212
	v_fmac_f32_e32 v213, v189, v213
	v_fmac_f32_e32 v214, v190, v214
	v_fmac_f32_e32 v215, v191, v215
	v_div_scale_f32 v216, vcc, 1.0, v192, 1.0
	v_mul_f32_e32 v224, v216, v208
	v_fma_f32 v184, -v200, v224, v216
	v_fmac_f32_e32 v224, v184, v208
	v_fma_f32 v216, -v200, v224, v216
	v_div_fmas_f32 v216, v216, v208, v224
	v_div_fixup_f32 v184, v216, v192, 1.0
	v_div_scale_f32 v217, vcc, 1.0, v193, 1.0
	v_mul_f32_e32 v225, v217, v209
	v_fma_f32 v185, -v201, v225, v217
	v_fmac_f32_e32 v225, v185, v209
	v_fma_f32 v217, -v201, v225, v217
	v_div_fmas_f32 v217, v217, v209, v225
	v_div_fixup_f32 v185, v217, v193, 1.0
	v_div_scale_f32 v218, vcc, 1.0, v194, 1.0
	v_mul_f32_e32 v226, v218, v210
	v_fma_f32 v186, -v202, v226, v218
	v_fmac_f32_e32 v226, v186, v210
	v_fma_f32 v218, -v202, v226, v218
	v_div_fmas_f32 v218, v218, v210, v226
	v_div_fixup_f32 v186, v218, v194, 1.0
	v_div_scale_f32 v219, vcc, 1.0, v195, 1.0
	v_mul_f32_e32 v227, v219, v211
	v_fma_f32 v187, -v203, v227, v219
	v_fmac_f32_e32 v227, v187, v211
	v_fma_f32 v219, -v203, v227, v219
	v_div_fmas_f32 v219, v219, v211, v227
	v_div_fixup_f32 v187, v219, v195, 1.0
	v_div_scale_f32 v220, vcc, 1.0, v196, 1.0
	v_mul_f32_e32 v228, v220, v212
	v_fma_f32 v188, -v204, v228, v220
	v_fmac_f32_e32 v228, v188, v212
	v_fma_f32 v220, -v204, v228, v220
	v_div_fmas_f32 v220, v220, v212, v228
	v_div_fixup_f32 v188, v220, v196, 1.0
	v_div_scale_f32 v221, vcc, 1.0, v197, 1.0
	v_mul_f32_e32 v229, v221, v213
	v_fma_f32 v189, -v205, v229, v221
	v_fmac_f32_e32 v229, v189, v213
	v_fma_f32 v221, -v205, v229, v221
	v_div_fmas_f32 v221, v221, v213, v229
	v_div_fixup_f32 v189, v221, v197, 1.0
	v_div_scale_f32 v222, vcc, 1.0, v198, 1.0
	v_mul_f32_e32 v230, v222, v214
	v_fma_f32 v190, -v206, v230, v222
	v_fmac_f32_e32 v230, v190, v214
	v_fma_f32 v222, -v206, v230, v222
	v_div_fmas_f32 v222, v222, v214, v230
	v_div_fixup_f32 v190, v222, v198, 1.0
	v_div_scale_f32 v223, vcc, 1.0, v199, 1.0
	v_mul_f32_e32 v231, v223, v215
	v_fma_f32 v191, -v207, v231, v223
	v_fmac_f32_e32 v231, v191, v215
	v_fma_f32 v223, -v207, v231, v223
	v_div_fmas_f32 v223, v223, v215, v231
	v_div_fixup_f32 v191, v223, v199, 1.0
	v_lshlrev_b32_e32 v192, 16, v156
	v_and_b32_e32 v193, 0xffff0000, v156
	v_lshlrev_b32_e32 v200, 16, v176
	v_and_b32_e32 v201, 0xffff0000, v176
	v_lshlrev_b32_e32 v194, 16, v157
	v_and_b32_e32 v195, 0xffff0000, v157
	v_lshlrev_b32_e32 v202, 16, v177
	v_and_b32_e32 v203, 0xffff0000, v177
	v_lshlrev_b32_e32 v196, 16, v158
	v_and_b32_e32 v197, 0xffff0000, v158
	v_lshlrev_b32_e32 v204, 16, v178
	v_and_b32_e32 v205, 0xffff0000, v178
	v_lshlrev_b32_e32 v198, 16, v159
	v_and_b32_e32 v199, 0xffff0000, v159
	v_lshlrev_b32_e32 v206, 16, v179
	v_and_b32_e32 v207, 0xffff0000, v179
	v_fma_f32 v184, v184, v200, v192
	v_fma_f32 v185, v185, v201, v193
	v_fma_f32 v186, v186, v202, v194
	v_fma_f32 v187, v187, v203, v195
	v_fma_f32 v188, v188, v204, v196
	v_fma_f32 v189, v189, v205, v197
	v_fma_f32 v190, v190, v206, v198
	v_fma_f32 v191, v191, v207, v199
	v_cvt_pk_bf16_f32 v216, v184, v185
	v_cvt_pk_bf16_f32 v217, v186, v187
	v_cvt_pk_bf16_f32 v218, v188, v189
	v_cvt_pk_bf16_f32 v219, v190, v191
	s_nop 1
	v_permlane16_swap_b32_e32 v216, v218
	v_permlane16_swap_b32_e32 v217, v219
	global_store_dwordx4 v248, v[216:219], s[26:27]
	s_waitcnt vmcnt(3)
	v_add_f32_e32 v184, v56, v136
	v_add_f32_e32 v185, v57, v137
	v_add_f32_e32 v186, v58, v138
	v_add_f32_e32 v187, v59, v139
	v_add_f32_e32 v188, v60, v140
	v_add_f32_e32 v189, v61, v141
	v_add_f32_e32 v190, v62, v142
	v_add_f32_e32 v191, v63, v143
	v_mul_f32_e32 v184, 0xbfb8aa3b, v184
	v_mul_f32_e32 v185, 0xbfb8aa3b, v185
	v_mul_f32_e32 v186, 0xbfb8aa3b, v186
	v_mul_f32_e32 v187, 0xbfb8aa3b, v187
	v_mul_f32_e32 v188, 0xbfb8aa3b, v188
	v_mul_f32_e32 v189, 0xbfb8aa3b, v189
	v_mul_f32_e32 v190, 0xbfb8aa3b, v190
	v_mul_f32_e32 v191, 0xbfb8aa3b, v191
	v_exp_f32_e32 v192, v184
	v_exp_f32_e32 v193, v185
	v_exp_f32_e32 v194, v186
	v_exp_f32_e32 v195, v187
	v_exp_f32_e32 v196, v188
	v_exp_f32_e32 v197, v189
	v_exp_f32_e32 v198, v190
	v_exp_f32_e32 v199, v191
	v_add_f32_e32 v192, 1.0, v192
	v_add_f32_e32 v193, 1.0, v193
	v_add_f32_e32 v194, 1.0, v194
	v_add_f32_e32 v195, 1.0, v195
	v_add_f32_e32 v196, 1.0, v196
	v_add_f32_e32 v197, 1.0, v197
	v_add_f32_e32 v198, 1.0, v198
	v_add_f32_e32 v199, 1.0, v199
	v_div_scale_f32 v200, s[76:77], v192, v192, 1.0
	v_div_scale_f32 v201, s[76:77], v193, v193, 1.0
	v_div_scale_f32 v202, s[76:77], v194, v194, 1.0
	v_div_scale_f32 v203, s[76:77], v195, v195, 1.0
	v_div_scale_f32 v204, s[76:77], v196, v196, 1.0
	v_div_scale_f32 v205, s[76:77], v197, v197, 1.0
	v_div_scale_f32 v206, s[76:77], v198, v198, 1.0
	v_div_scale_f32 v207, s[76:77], v199, v199, 1.0
	v_rcp_f32_e32 v208, v200
	v_rcp_f32_e32 v209, v201
	v_rcp_f32_e32 v210, v202
	v_rcp_f32_e32 v211, v203
	v_rcp_f32_e32 v212, v204
	v_rcp_f32_e32 v213, v205
	v_rcp_f32_e32 v214, v206
	v_rcp_f32_e32 v215, v207
	v_fma_f32 v184, -v200, v208, 1.0
	v_fma_f32 v185, -v201, v209, 1.0
	v_fma_f32 v186, -v202, v210, 1.0
	v_fma_f32 v187, -v203, v211, 1.0
	v_fma_f32 v188, -v204, v212, 1.0
	v_fma_f32 v189, -v205, v213, 1.0
	v_fma_f32 v190, -v206, v214, 1.0
	v_fma_f32 v191, -v207, v215, 1.0
	v_fmac_f32_e32 v208, v184, v208
	v_fmac_f32_e32 v209, v185, v209
	v_fmac_f32_e32 v210, v186, v210
	v_fmac_f32_e32 v211, v187, v211
	v_fmac_f32_e32 v212, v188, v212
	v_fmac_f32_e32 v213, v189, v213
	v_fmac_f32_e32 v214, v190, v214
	v_fmac_f32_e32 v215, v191, v215
	v_div_scale_f32 v216, vcc, 1.0, v192, 1.0
	v_mul_f32_e32 v224, v216, v208
	v_fma_f32 v184, -v200, v224, v216
	v_fmac_f32_e32 v224, v184, v208
	v_fma_f32 v216, -v200, v224, v216
	v_div_fmas_f32 v216, v216, v208, v224
	v_div_fixup_f32 v184, v216, v192, 1.0
	v_div_scale_f32 v217, vcc, 1.0, v193, 1.0
	v_mul_f32_e32 v225, v217, v209
	v_fma_f32 v185, -v201, v225, v217
	v_fmac_f32_e32 v225, v185, v209
	v_fma_f32 v217, -v201, v225, v217
	v_div_fmas_f32 v217, v217, v209, v225
	v_div_fixup_f32 v185, v217, v193, 1.0
	v_div_scale_f32 v218, vcc, 1.0, v194, 1.0
	v_mul_f32_e32 v226, v218, v210
	v_fma_f32 v186, -v202, v226, v218
	v_fmac_f32_e32 v226, v186, v210
	v_fma_f32 v218, -v202, v226, v218
	v_div_fmas_f32 v218, v218, v210, v226
	v_div_fixup_f32 v186, v218, v194, 1.0
	v_div_scale_f32 v219, vcc, 1.0, v195, 1.0
	v_mul_f32_e32 v227, v219, v211
	v_fma_f32 v187, -v203, v227, v219
	v_fmac_f32_e32 v227, v187, v211
	v_fma_f32 v219, -v203, v227, v219
	v_div_fmas_f32 v219, v219, v211, v227
	v_div_fixup_f32 v187, v219, v195, 1.0
	v_div_scale_f32 v220, vcc, 1.0, v196, 1.0
	v_mul_f32_e32 v228, v220, v212
	v_fma_f32 v188, -v204, v228, v220
	v_fmac_f32_e32 v228, v188, v212
	v_fma_f32 v220, -v204, v228, v220
	v_div_fmas_f32 v220, v220, v212, v228
	v_div_fixup_f32 v188, v220, v196, 1.0
	v_div_scale_f32 v221, vcc, 1.0, v197, 1.0
	v_mul_f32_e32 v229, v221, v213
	v_fma_f32 v189, -v205, v229, v221
	v_fmac_f32_e32 v229, v189, v213
	v_fma_f32 v221, -v205, v229, v221
	v_div_fmas_f32 v221, v221, v213, v229
	v_div_fixup_f32 v189, v221, v197, 1.0
	v_div_scale_f32 v222, vcc, 1.0, v198, 1.0
	v_mul_f32_e32 v230, v222, v214
	v_fma_f32 v190, -v206, v230, v222
	v_fmac_f32_e32 v230, v190, v214
	v_fma_f32 v222, -v206, v230, v222
	v_div_fmas_f32 v222, v222, v214, v230
	v_div_fixup_f32 v190, v222, v198, 1.0
	v_div_scale_f32 v223, vcc, 1.0, v199, 1.0
	v_mul_f32_e32 v231, v223, v215
	v_fma_f32 v191, -v207, v231, v223
	v_fmac_f32_e32 v231, v191, v215
	v_fma_f32 v223, -v207, v231, v223
	v_div_fmas_f32 v223, v223, v215, v231
	v_div_fixup_f32 v191, v223, v199, 1.0
	v_lshlrev_b32_e32 v192, 16, v160
	v_and_b32_e32 v193, 0xffff0000, v160
	v_lshlrev_b32_e32 v200, 16, v180
	v_and_b32_e32 v201, 0xffff0000, v180
	v_lshlrev_b32_e32 v194, 16, v161
	v_and_b32_e32 v195, 0xffff0000, v161
	v_lshlrev_b32_e32 v202, 16, v181
	v_and_b32_e32 v203, 0xffff0000, v181
	v_lshlrev_b32_e32 v196, 16, v162
	v_and_b32_e32 v197, 0xffff0000, v162
	v_lshlrev_b32_e32 v204, 16, v182
	v_and_b32_e32 v205, 0xffff0000, v182
	v_lshlrev_b32_e32 v198, 16, v163
	v_and_b32_e32 v199, 0xffff0000, v163
	v_lshlrev_b32_e32 v206, 16, v183
	v_and_b32_e32 v207, 0xffff0000, v183
	v_fma_f32 v184, v184, v200, v192
	v_fma_f32 v185, v185, v201, v193
	v_fma_f32 v186, v186, v202, v194
	v_fma_f32 v187, v187, v203, v195
	v_fma_f32 v188, v188, v204, v196
	v_fma_f32 v189, v189, v205, v197
	v_fma_f32 v190, v190, v206, v198
	v_fma_f32 v191, v191, v207, v199
	v_cvt_pk_bf16_f32 v220, v184, v185
	v_cvt_pk_bf16_f32 v221, v186, v187
	v_cvt_pk_bf16_f32 v222, v188, v189
	v_cvt_pk_bf16_f32 v223, v190, v191
	s_nop 1
	v_permlane16_swap_b32_e32 v220, v222
	v_permlane16_swap_b32_e32 v221, v223
	global_store_dwordx4 v248, v[220:223], s[26:27] offset:64
	s_cmp_eq_u32 s83, 1
	s_cbranch_scc1 .Lp6d_epdone
	s_cmp_eq_u32 s95, 1
	s_cbranch_scc0 .Lp6d_epdone
	v_mov_b32_e32 v0, v64
	v_mov_b32_e32 v1, v65
	v_mov_b32_e32 v2, v66
	v_mov_b32_e32 v3, v67
	v_mov_b32_e32 v4, v68
	v_mov_b32_e32 v5, v69
	v_mov_b32_e32 v6, v70
	v_mov_b32_e32 v7, v71
	v_mov_b32_e32 v8, v72
	v_mov_b32_e32 v9, v73
	v_mov_b32_e32 v10, v74
	v_mov_b32_e32 v11, v75
	v_mov_b32_e32 v12, v76
	v_mov_b32_e32 v13, v77
	v_mov_b32_e32 v14, v78
	v_mov_b32_e32 v15, v79
	v_mov_b32_e32 v16, v80
	v_mov_b32_e32 v17, v81
	v_mov_b32_e32 v18, v82
	v_mov_b32_e32 v19, v83
	v_mov_b32_e32 v20, v84
	v_mov_b32_e32 v21, v85
	v_mov_b32_e32 v22, v86
	v_mov_b32_e32 v23, v87
	v_mov_b32_e32 v24, v88
	v_mov_b32_e32 v25, v89
	v_mov_b32_e32 v26, v90
	v_mov_b32_e32 v27, v91
	v_mov_b32_e32 v28, v92
	v_mov_b32_e32 v29, v93
	v_mov_b32_e32 v30, v94
	v_mov_b32_e32 v31, v95
	v_mov_b32_e32 v32, v96
	v_mov_b32_e32 v33, v97
	v_mov_b32_e32 v34, v98
	v_mov_b32_e32 v35, v99
	v_mov_b32_e32 v36, v100
	v_mov_b32_e32 v37, v101
	v_mov_b32_e32 v38, v102
	v_mov_b32_e32 v39, v103
	v_mov_b32_e32 v40, v104
	v_mov_b32_e32 v41, v105
	v_mov_b32_e32 v42, v106
	v_mov_b32_e32 v43, v107
	v_mov_b32_e32 v44, v108
	v_mov_b32_e32 v45, v109
	v_mov_b32_e32 v46, v110
	v_mov_b32_e32 v47, v111
	v_mov_b32_e32 v48, v112
	v_mov_b32_e32 v49, v113
	v_mov_b32_e32 v50, v114
	v_mov_b32_e32 v51, v115
	v_mov_b32_e32 v52, v116
	v_mov_b32_e32 v53, v117
	v_mov_b32_e32 v54, v118
	v_mov_b32_e32 v55, v119
	v_mov_b32_e32 v56, v120
	v_mov_b32_e32 v57, v121
	v_mov_b32_e32 v58, v122
	v_mov_b32_e32 v59, v123
	v_mov_b32_e32 v60, v124
	v_mov_b32_e32 v61, v125
	v_mov_b32_e32 v62, v126
	v_mov_b32_e32 v63, v127
	s_mov_b32 s83, 1
	s_branch .Lp6d_ep

.LBB0_597:
	s_cmp_gt_i32 s54, 8
	s_cselect_b64 s[6:7], -1, 0
	s_cmp_lt_i32 s55, 9
	s_cselect_b64 s[8:9], -1, 0
	s_or_b64 s[6:7], s[6:7], s[8:9]
	s_and_b64 vcc, exec, s[6:7]
	s_cbranch_vccnz .LBB0_655
	s_cmpk_gt_i32 s2, 0xfff
	s_cbranch_scc1 .LBB0_601
	s_load_dwordx2 s[6:7], s[0:1], 0xf0
	s_load_dwordx2 s[8:9], s[0:1], 0x70
	v_lshlrev_b32_e32 v0, 2, v168
	v_and_b32_e32 v17, 0xfc, v0
	v_lshlrev_b32_e32 v18, 2, v17
	v_mbcnt_lo_u32_b32 v20, -1, 0
	s_waitcnt lgkmcnt(0)
	global_load_dwordx4 v[0:3], v18, s[8:9]
	global_load_dwordx4 v[4:7], v18, s[8:9] offset:1024
	global_load_dwordx4 v[8:11], v18, s[8:9] offset:2048
	global_load_dwordx4 v[12:15], v18, s[8:9] offset:3072
	v_mbcnt_hi_u32_b32 v22, -1, v20
	v_lshlrev_b32_e32 v20, 1, v17
	v_and_b32_e32 v17, 64, v22
	v_xor_b32_e32 v23, 32, v22
	v_add_u32_e32 v17, 64, v17
	v_xor_b32_e32 v26, 16, v22
	v_cmp_lt_i32_e32 vcc, v23, v17
	v_xor_b32_e32 v27, 8, v22
	s_load_dwordx2 s[10:11], s[0:1], 0xe0
	v_cndmask_b32_e32 v23, v22, v23, vcc
	v_cmp_lt_i32_e32 vcc, v26, v17
	v_xor_b32_e32 v28, 4, v22
	v_xor_b32_e32 v29, 2, v22
	v_cndmask_b32_e32 v31, v22, v26, vcc
	v_cmp_lt_i32_e32 vcc, v27, v17
	v_xor_b32_e32 v30, 1, v22
	v_mov_b32_e32 v19, 0
	v_cndmask_b32_e32 v32, v22, v27, vcc
	v_cmp_lt_i32_e32 vcc, v28, v17
	v_mov_b32_e32 v21, v19
	s_mov_b32 s90, s2
	s_cmp_eq_u32 s52, 0x200
	s_cbranch_scc0 .Lp8_nomap
	s_and_b32 s90, s2, 7
	s_lshl_b32 s90, s90, 9
	s_lshr_b32 s91, s2, 3
	s_add_u32 s90, s90, s91
.Lp8_nomap:
	v_lshl_add_u32 v16, s90, 2, v169
	v_cndmask_b32_e32 v33, v22, v28, vcc
	v_cmp_lt_i32_e32 vcc, v29, v17
	s_lshl_b32 s3, s52, 2
	s_cmp_eq_u32 s52, 0x200
	s_cselect_b32 s3, 0x100, s3
	v_mov_b32_e32 v24, 0x358637bd
	v_cndmask_b32_e32 v34, v22, v29, vcc
	v_cmp_lt_i32_e32 vcc, v30, v17
	s_mov_b32 s8, 0x800000
	s_movk_i32 s9, 0x7fff
	v_cndmask_b32_e32 v17, v22, v30, vcc
	v_mov_b32_e32 v25, 1
	s_waitcnt lgkmcnt(0)
	v_lshl_add_u64 v[18:19], s[10:11], 0, v[18:19]
	v_lshl_add_u64 v[20:21], s[6:7], 0, v[20:21]
	v_lshlrev_b32_e32 v26, 2, v23
	v_lshlrev_b32_e32 v27, 2, v31
	v_lshlrev_b32_e32 v28, 2, v32
	v_lshlrev_b32_e32 v29, 2, v33
	v_lshlrev_b32_e32 v30, 2, v34
	v_lshlrev_b32_e32 v31, 2, v17
	s_mov_b32 s6, s2
	s_waitcnt vmcnt(0)
	v_mov_b32_e32 v22, v1
	v_mov_b32_e32 v23, v3
	v_mov_b32_e32 v1, v2
	v_mov_b32_e32 v2, v5
	v_mov_b32_e32 v3, v7
	v_mov_b32_e32 v5, v6
	v_mov_b32_e32 v6, v9
	v_mov_b32_e32 v7, v11
	v_mov_b32_e32 v9, v10
	v_mov_b32_e32 v10, v13
	v_mov_b32_e32 v11, v15
	v_mov_b32_e32 v13, v14
